# phase-0 f32 weight loads non-temporal (read once); DPP gate-scalar scan merged with the gate-epilogue load hoists
# speedup vs baseline: 1.0080x; 1.0023x over previous
; __device__ __forceinline__ void transpose_item(const float* src, int ldsrc, bf16_t* dst, int lddst, int kt, int ntile, LAS float* scr, int lane, const float* kscale = nullptr) {
;     const int k0 = kt * 64, n0 = ntile * 64, l16 = lane & 15, l4 = lane >> 4;
;     f32x4 tv[16];
; #pragma unroll
;     for (int i = 0; i < 16; ++i) tv[i] = *(const f32x4*)(src + (size_t)(k0 + l4 + 4 * i) * ldsrc + n0 + 4 * l16);
;     if (kscale) {
; #pragma unroll
;         for (int i = 0; i < 16; ++i) tv[i] *= kscale[k0 + l4 + 4 * i];
;     }
; #pragma unroll
;     for (int i = 0; i < 16; ++i) { const int kk = l4 + 4 * i; const f32x4 v = tv[i];
; __device__ __forceinline__ void phase0(const Params& p, LAS unsigned char* lds, const bool do_gemv = true) {
;     ...
;     for (int it = gw; it < NITEMS; it += NGW) {
;         int r = it;
;         if (r < I_GEMV) { if (do_gemv) gemv_item(p, MOD, r, scr, lane); continue; } r -= I_GEMV;
;         if (r < I_AIN) { transpose_item(p.a_w_in, INA, (bf16_t*)(ws + OFF_W_AIN), 2048, r / 96, r % 96, scr, lane); continue; } r -= I_AIN;
;         if (r < I_SQ) { transpose_item(p.a_w_out, 2048, (bf16_t*)(ws + OFF_W_AOUT), 2048, r / 32, r % 32, scr, lane, p.a_norm_g); continue; } r -= I_SQ;
;         if (r < I_SQ) { transpose_item(p.b_w_out, 2048, (bf16_t*)(ws + OFF_W_BOUT), 2048, r / 32, r % 32, scr, lane); continue; } r -= I_SQ;
;         if (r < I_BIN) { transpose_item(p.b_w_in, 4096, (bf16_t*)(ws + OFF_W_BIN), 2048, r / 64, r % 64, scr, lane); continue; } r -= I_BIN;
;         if (r < 2 * I_MLP) { const int l = r / I_MLP, q = r % I_MLP; transpose_item(p.mlp_w1 + (size_t)l * DM * DFF, DFF, (bf16_t*)(ws + OFF_W_1) + (size_t)l * DFF * DM, DM, q / 128, q % 128, scr, lane); continue; } r -= 2 * I_MLP;
;         if (r < 2 * I_MLP) { const int l = r / I_MLP, q = r % I_MLP; transpose_item(p.mlp_w2 + (size_t)l * DM * DFF, DM, (bf16_t*)(ws + OFF_W_2) + (size_t)l * DFF * DM, DFF, q / 32, q % 32, scr, lane); continue; } r -= 2 * I_MLP;
;         { const int sub = r >> 3, q = r & 7, kt = q >> 1, ntile = q & 1, nb = sub >> 2, gate = (sub >> 1) & 1, dh = sub & 1;
;           const float* src = (gate ? p.b_w_ri : p.b_w_ra) + (size_t)nb * 65536 + dh * 128;
;           bf16_t* dst = (bf16_t*)(ws + OFF_W_GATE) + (size_t)((nb * 2 + dh) * 256 + gate * 128) * 256;
;           transpose_item(src, 256, dst, 256, kt, ntile, scr, lane); }
.LBB0_31:
	s_cmpk_gt_i32 s12, 0x17ff
	s_mov_b64 s[0:1], -1
	s_cbranch_scc0 .LBB0_59
	s_cmpk_gt_u32 s12, 0x23ff
	s_cbranch_scc0 .LBB0_56
	s_cmpk_gt_u32 s12, 0x27ff
	s_cbranch_scc0 .LBB0_51
	s_cmpk_gt_u32 s12, 0x2bff
	s_cbranch_scc0 .LBB0_48
	s_cmpk_gt_u32 s12, 0x33ff
	s_cbranch_scc0 .LBB0_45
	s_cmpk_gt_u32 s12, 0x53ff
	s_cbranch_scc0 .LBB0_42
	s_cmpk_gt_u32 s12, 0x73ff
	s_cbranch_scc0 .LBB0_39
	s_add_i32 s0, s12, 0xffff8c00
	s_mov_b64 s[56:57], s[80:81]
	s_lshr_b32 s2, s0, 5
	s_bfe_u32 s10, s12, 0x10004
	s_bfe_u32 s11, s12, 0x10003
	s_mov_b64 s[58:59], s[82:83]
	s_mov_b64 s[60:61], s[84:85]
	s_mov_b64 s[62:63], s[86:87]
	s_mov_b64 s[66:67], s[90:91]
	s_mov_b64 s[68:69], s[92:93]
	v_readlane_b32 s80, v254, 8
	s_cmp_eq_u32 s10, 0
	v_readlane_b32 s86, v254, 14
	v_readlane_b32 s87, v254, 15
	v_readlane_b32 s90, v254, 18
	v_readlane_b32 s91, v254, 19
	s_cselect_b32 s53, s87, s91
	s_cselect_b32 s54, s86, s90
	s_lshl_b64 s[0:1], s[2:3], 18
	s_add_u32 s0, s54, s0
	s_addc_u32 s1, s53, s1
	s_lshl_b32 s53, s11, 9
	s_add_u32 s53, s0, s53
	s_addc_u32 s54, s1, 0
	s_lshl_b32 s0, s2, 9
	s_lshl_b32 s1, s11, 8
	s_or_b32 s0, s0, s1
	s_lshl_b32 s1, s10, 7
	s_or_b32 s2, s0, s1
	s_lshl_b64 s[0:1], s[2:3], 9
	s_add_u32 s2, s14, s0
	s_addc_u32 s1, s15, s1
	s_lshl_b32 s0, s12, 5
	s_and_b32 s55, s0, 0xc0
	s_lshl_b32 s0, s12, 6
	s_and_b32 s0, s0, 64
	s_lshl_b32 s10, s0, 2
	s_add_u32 s10, s53, s10
	v_or_b32_e32 v2, s55, v88
	s_addc_u32 s11, s54, 0
	v_mov_b32_e32 v85, v65
	v_lshl_add_u64 v[0:1], s[10:11], 0, v[84:85]
	v_lshlrev_b32_e32 v64, 10, v2
	v_lshl_add_u64 v[60:61], v[0:1], 0, v[64:65]
	s_movk_i32 s10, 0x2000
	v_add_co_u32_e32 v8, vcc, s10, v60
	s_movk_i32 s10, 0x4000
	s_nop 0
	v_addc_co_u32_e32 v9, vcc, 0, v61, vcc
	v_add_co_u32_e32 v16, vcc, s10, v60
	s_mov_b32 s10, 0xa000
	s_nop 0
	v_addc_co_u32_e32 v17, vcc, 0, v61, vcc
	v_add_co_u32_e32 v24, vcc, s20, v60
	global_load_dwordx4 v[0:3], v[60:61], off nt
	s_nop 0
	v_addc_co_u32_e32 v25, vcc, 0, v61, vcc
	v_add_co_u32_e32 v32, vcc, s21, v60
	global_load_dwordx4 v[4:7], v[8:9], off offset:-4096 nt
	s_nop 0
	global_load_dwordx4 v[8:11], v[8:9], off nt
	v_addc_co_u32_e32 v33, vcc, 0, v61, vcc
	v_add_co_u32_e32 v40, vcc, s10, v60
	global_load_dwordx4 v[12:15], v[16:17], off offset:-4096 nt
	s_nop 0
	global_load_dwordx4 v[16:19], v[16:17], off nt
	s_nop 0
	global_load_dwordx4 v[20:23], v[24:25], off offset:-4096 nt
	s_nop 0
	global_load_dwordx4 v[24:27], v[24:25], off nt
	s_nop 0
	global_load_dwordx4 v[28:31], v[32:33], off offset:-4096 nt
	s_nop 0
	global_load_dwordx4 v[32:35], v[32:33], off nt
	v_addc_co_u32_e32 v41, vcc, 0, v61, vcc
	global_load_dwordx4 v[36:39], v[40:41], off offset:-4096 nt
	s_nop 0
	global_load_dwordx4 v[40:43], v[40:41], off nt
	v_add_co_u32_e32 v48, vcc, s22, v60
	s_mov_b32 s10, 0xe000
	s_nop 0
	v_addc_co_u32_e32 v49, vcc, 0, v61, vcc
	global_load_dwordx4 v[44:47], v[48:49], off offset:-4096 nt
	s_nop 0
	global_load_dwordx4 v[48:51], v[48:49], off nt
	v_add_co_u32_e32 v56, vcc, s10, v60
	s_mov_b32 s10, 0xf000
	s_nop 0
	v_addc_co_u32_e32 v57, vcc, 0, v61, vcc
	global_load_dwordx4 v[52:55], v[56:57], off offset:-4096 nt
	s_nop 0
	global_load_dwordx4 v[56:59], v[56:57], off nt
	v_add_co_u32_e32 v60, vcc, s10, v60
	v_add_u32_e32 v64, 0x2490, v89
	s_nop 0
	v_addc_co_u32_e32 v61, vcc, 0, v61, vcc
	global_load_dwordx4 v[60:63], v[60:61], off nt
	v_add_u32_e32 v85, 0x2498, v89
	s_lshl_b32 s10, s55, 1
	s_add_u32 s10, s2, s10
	s_addc_u32 s11, s1, 0
	v_readlane_b32 s81, v254, 9
	v_readlane_b32 s82, v254, 10
	v_readlane_b32 s83, v254, 11
	v_readlane_b32 s84, v254, 12
	v_readlane_b32 s85, v254, 13
	v_readlane_b32 s92, v254, 20
	v_readlane_b32 s93, v254, 21
	s_mov_b64 s[86:87], s[62:63]
	v_readlane_b32 s88, v254, 16
	v_readlane_b32 s89, v254, 17
	v_readlane_b32 s94, v254, 22
	v_readlane_b32 s95, v254, 23
	s_mov_b64 s[84:85], s[60:61]
	s_mov_b64 s[82:83], s[58:59]
	s_waitcnt vmcnt(15)
	ds_write2_b32 v89, v0, v1 offset1:1
	ds_write2_b32 v89, v2, v3 offset0:2 offset1:3
	s_waitcnt vmcnt(14)
	ds_write2_b32 v103, v4, v5 offset1:1
	ds_write2_b32 v104, v6, v7 offset1:1
	s_waitcnt vmcnt(13)
	ds_write2_b32 v105, v8, v9 offset1:1
	ds_write2_b32 v106, v10, v11 offset1:1
	s_waitcnt vmcnt(12)
	ds_write2_b32 v107, v12, v13 offset1:1
	ds_write2_b32 v108, v14, v15 offset1:1
	s_waitcnt vmcnt(11)
	ds_write2_b32 v109, v16, v17 offset1:1
	ds_write2_b32 v110, v18, v19 offset1:1
	s_waitcnt vmcnt(10)
	ds_write2_b32 v111, v20, v21 offset1:1
	ds_write2_b32 v112, v22, v23 offset1:1
	s_waitcnt vmcnt(9)
	ds_write2_b32 v113, v24, v25 offset1:1
	ds_write2_b32 v114, v26, v27 offset1:1
	s_waitcnt vmcnt(8)
	ds_write2_b32 v115, v28, v29 offset1:1
	ds_write2_b32 v116, v30, v31 offset1:1
	s_waitcnt vmcnt(7)
	ds_write2_b32 v117, v32, v33 offset1:1
	ds_write2_b32 v118, v34, v35 offset1:1
	s_waitcnt vmcnt(6)
	ds_write2_b32 v64, v36, v37 offset1:1
	ds_write2_b32 v85, v38, v39 offset1:1
	v_add_u32_e32 v0, 0x28a0, v89
	s_waitcnt vmcnt(5)
	ds_write2_b32 v0, v40, v41 offset1:1
	v_add_u32_e32 v0, 0x28a8, v89
	ds_write2_b32 v0, v42, v43 offset1:1
	v_add_u32_e32 v0, 0x2cb0, v89
	s_waitcnt vmcnt(4)
	ds_write2_b32 v0, v44, v45 offset1:1
	v_add_u32_e32 v0, 0x2cb8, v89
	ds_write2_b32 v0, v46, v47 offset1:1
	v_add_u32_e32 v0, 0x30c0, v89
	s_waitcnt vmcnt(3)
	ds_write2_b32 v0, v48, v49 offset1:1
	v_add_u32_e32 v0, 0x30c8, v89
	ds_write2_b32 v0, v50, v51 offset1:1
	v_add_u32_e32 v0, 0x34d0, v89
	s_waitcnt vmcnt(2)
	ds_write2_b32 v0, v52, v53 offset1:1
	v_add_u32_e32 v0, 0x34d8, v89
	ds_write2_b32 v0, v54, v55 offset1:1
	v_add_u32_e32 v0, 0x38e0, v89
	s_waitcnt vmcnt(1)
	ds_write2_b32 v0, v56, v57 offset1:1
	v_add_u32_e32 v0, 0x38e8, v89
	ds_write2_b32 v0, v58, v59 offset1:1
	v_add_u32_e32 v0, 0x3cf0, v89
	s_waitcnt vmcnt(0)
; #define LAS __attribute__((address_space(3)))
; __device__ __forceinline__ unsigned cvt_pk_bf16(float lo, float hi) { const bf16x2_t r = __builtin_convertvector((f32x2){lo, hi}, bf16x2_t); return __builtin_bit_cast(unsigned, r); }
; #define LDS_FENCE() asm volatile("s_waitcnt lgkmcnt(0)" ::: "memory")
; __device__ __forceinline__ void transpose_item(const float* src, int ldsrc, bf16_t* dst, int lddst, int kt, int ntile, LAS float* scr, int lane, const float* kscale = nullptr) {
;     ...
;     LDS_FENCE();
;     const int c = lane & 7;
; #pragma unroll
;     for (int j = 0; j < 8; ++j) { const int n = (lane >> 3) + 8 * j; const LAS float* s = scr + (8 * c) * 65 + n;
;         u32x4 o; o.x = cvt_pk_bf16(s[0], s[65]); o.y = cvt_pk_bf16(s[2 * 65], s[3 * 65]); o.z = cvt_pk_bf16(s[4 * 65], s[5 * 65]); o.w = cvt_pk_bf16(s[6 * 65], s[7 * 65]);
;         *(u32x4*)(dst + (size_t)(n0 + n) * lddst + k0 + 8 * c) = o; }
;     LDS_FENCE();
	ds_write2_b32 v0, v60, v61 offset1:1
	v_add_u32_e32 v0, 0x3cf8, v89
	ds_write2_b32 v0, v62, v63 offset1:1
	s_waitcnt lgkmcnt(0)
	v_add_u32_e32 v24, 0x400, v91
	ds_read2_b32 v[4:5], v91 offset0:65 offset1:73
	ds_read2_b32 v[6:7], v91 offset1:8
	ds_read2_b32 v[8:9], v91 offset0:130 offset1:138
	ds_read2_b32 v[10:11], v91 offset0:195 offset1:203
	ds_read2_b32 v[12:13], v24 offset0:4 offset1:12
	ds_read2_b32 v[14:15], v24 offset0:69 offset1:77
	ds_read2_b32 v[16:17], v24 offset0:134 offset1:142
	ds_read2_b32 v[18:19], v24 offset0:199 offset1:207
	v_lshlrev_b32_e32 v64, 1, v66
	s_waitcnt lgkmcnt(6)
	v_cvt_pk_bf16_f32 v0, v6, v4
	v_or_b32_e32 v4, s0, v90
	v_lshl_add_u64 v[20:21], s[10:11], 0, v[64:65]
	v_lshlrev_b32_e32 v64, 9, v4
	s_waitcnt lgkmcnt(4)
	v_cvt_pk_bf16_f32 v1, v8, v10
	s_waitcnt lgkmcnt(2)
	v_cvt_pk_bf16_f32 v2, v12, v14
	s_waitcnt lgkmcnt(0)
	v_cvt_pk_bf16_f32 v3, v16, v18
	v_lshl_add_u64 v[22:23], v[20:21], 0, v[64:65]
	global_store_dwordx4 v[22:23], v[0:3], off
	v_or_b32_e32 v4, s0, v92
	v_lshlrev_b32_e32 v64, 9, v4
	v_cvt_pk_bf16_f32 v0, v7, v5
	v_cvt_pk_bf16_f32 v1, v9, v11
	v_cvt_pk_bf16_f32 v2, v13, v15
	v_cvt_pk_bf16_f32 v3, v17, v19
	ds_read2_b32 v[6:7], v91 offset0:81 offset1:89
	ds_read2_b32 v[8:9], v91 offset0:16 offset1:24
	ds_read2_b32 v[10:11], v91 offset0:146 offset1:154
	ds_read2_b32 v[12:13], v91 offset0:211 offset1:219
	ds_read2_b32 v[14:15], v24 offset0:20 offset1:28
	ds_read2_b32 v[16:17], v24 offset0:85 offset1:93
	ds_read2_b32 v[18:19], v24 offset0:150 offset1:158
	ds_read2_b32 v[22:23], v24 offset0:215 offset1:223
	v_lshl_add_u64 v[4:5], v[20:21], 0, v[64:65]
	global_store_dwordx4 v[4:5], v[0:3], off
	v_or_b32_e32 v4, s0, v93
	v_lshlrev_b32_e32 v64, 9, v4
	s_waitcnt lgkmcnt(6)
	v_cvt_pk_bf16_f32 v0, v8, v6
	s_waitcnt lgkmcnt(4)
	v_cvt_pk_bf16_f32 v1, v10, v12
	s_waitcnt lgkmcnt(2)
	v_cvt_pk_bf16_f32 v2, v14, v16
	s_waitcnt lgkmcnt(0)
	v_cvt_pk_bf16_f32 v3, v18, v22
	v_lshl_add_u64 v[4:5], v[20:21], 0, v[64:65]
	global_store_dwordx4 v[4:5], v[0:3], off
	v_or_b32_e32 v4, s0, v94
	v_lshlrev_b32_e32 v64, 9, v4
	v_cvt_pk_bf16_f32 v0, v9, v7
	v_cvt_pk_bf16_f32 v1, v11, v13
	v_cvt_pk_bf16_f32 v2, v15, v17
	v_cvt_pk_bf16_f32 v3, v19, v23
	ds_read2_b32 v[6:7], v91 offset0:32 offset1:40
	ds_read2_b32 v[8:9], v91 offset0:97 offset1:105
	ds_read2_b32 v[10:11], v91 offset0:162 offset1:170
	ds_read2_b32 v[12:13], v91 offset0:227 offset1:235
	ds_read2_b32 v[14:15], v24 offset0:36 offset1:44
	ds_read2_b32 v[16:17], v24 offset0:101 offset1:109
	ds_read2_b32 v[18:19], v24 offset0:166 offset1:174
	ds_read2_b32 v[22:23], v24 offset0:231 offset1:239
	v_lshl_add_u64 v[4:5], v[20:21], 0, v[64:65]
	global_store_dwordx4 v[4:5], v[0:3], off
	v_or_b32_e32 v4, s0, v95
	v_lshlrev_b32_e32 v64, 9, v4
	s_waitcnt lgkmcnt(6)
	v_cvt_pk_bf16_f32 v0, v6, v8
	s_waitcnt lgkmcnt(4)
	v_cvt_pk_bf16_f32 v1, v10, v12
	s_waitcnt lgkmcnt(2)
	v_cvt_pk_bf16_f32 v2, v14, v16
	s_waitcnt lgkmcnt(0)
	v_cvt_pk_bf16_f32 v3, v18, v22
	v_lshl_add_u64 v[4:5], v[20:21], 0, v[64:65]
	global_store_dwordx4 v[4:5], v[0:3], off
	v_or_b32_e32 v4, s0, v96
	v_lshlrev_b32_e32 v64, 9, v4
	v_cvt_pk_bf16_f32 v0, v7, v9
	v_cvt_pk_bf16_f32 v1, v11, v13
	v_cvt_pk_bf16_f32 v2, v15, v17
	v_cvt_pk_bf16_f32 v3, v19, v23
	ds_read2_b32 v[6:7], v91 offset0:48 offset1:56
	ds_read2_b32 v[8:9], v91 offset0:113 offset1:121
	ds_read2_b32 v[10:11], v91 offset0:178 offset1:186
	ds_read2_b32 v[12:13], v91 offset0:243 offset1:251
	ds_read2_b32 v[14:15], v24 offset0:52 offset1:60
	ds_read2_b32 v[16:17], v24 offset0:117 offset1:125
	ds_read2_b32 v[18:19], v24 offset0:182 offset1:190
	ds_read2_b32 v[22:23], v24 offset0:247 offset1:255
	v_lshl_add_u64 v[4:5], v[20:21], 0, v[64:65]
	global_store_dwordx4 v[4:5], v[0:3], off
	v_or_b32_e32 v4, s0, v97
	v_lshlrev_b32_e32 v64, 9, v4
	s_waitcnt lgkmcnt(6)
	v_cvt_pk_bf16_f32 v0, v6, v8
	s_waitcnt lgkmcnt(4)
	v_cvt_pk_bf16_f32 v1, v10, v12
	s_waitcnt lgkmcnt(2)
	v_cvt_pk_bf16_f32 v2, v14, v16
	s_waitcnt lgkmcnt(0)
	v_cvt_pk_bf16_f32 v3, v18, v22
	v_lshl_add_u64 v[4:5], v[20:21], 0, v[64:65]
	global_store_dwordx4 v[4:5], v[0:3], off
	v_or_b32_e32 v4, s0, v98
	v_lshlrev_b32_e32 v64, 9, v4
	v_cvt_pk_bf16_f32 v0, v7, v9
	v_cvt_pk_bf16_f32 v1, v11, v13
	v_cvt_pk_bf16_f32 v2, v15, v17
	v_cvt_pk_bf16_f32 v3, v19, v23
	v_lshl_add_u64 v[4:5], v[20:21], 0, v[64:65]
	global_store_dwordx4 v[4:5], v[0:3], off
	s_waitcnt lgkmcnt(0)
	s_mov_b64 s[80:81], s[56:57]
	s_mov_b64 s[90:91], s[66:67]
	s_mov_b64 s[92:93], s[68:69]
	s_mov_b64 s[0:1], 0
; #define LAS __attribute__((address_space(3)))
; __device__ __forceinline__ void transpose_item(const float* src, int ldsrc, bf16_t* dst, int lddst, int kt, int ntile, LAS float* scr, int lane, const float* kscale = nullptr) {
;     const int k0 = kt * 64, n0 = ntile * 64, l16 = lane & 15, l4 = lane >> 4;
;     f32x4 tv[16];
; #pragma unroll
;     for (int i = 0; i < 16; ++i) tv[i] = *(const f32x4*)(src + (size_t)(k0 + l4 + 4 * i) * ldsrc + n0 + 4 * l16);
;     if (kscale) {
; #pragma unroll
;         for (int i = 0; i < 16; ++i) tv[i] *= kscale[k0 + l4 + 4 * i];
;     }
; #pragma unroll
;     for (int i = 0; i < 16; ++i) { const int kk = l4 + 4 * i; const f32x4 v = tv[i];
;         LAS float* d = scr + kk * 65 + 4 * l16; d[0] = v[0]; d[1] = v[1]; d[2] = v[2]; d[3] = v[3]; }
; __device__ __forceinline__ void phase0(const Params& p, LAS unsigned char* lds, const bool do_gemv = true) {
;     ...
;         if (r < 2 * I_MLP) { const int l = r / I_MLP, q = r % I_MLP; transpose_item(p.mlp_w2 + (size_t)l * DM * DFF, DM, (bf16_t*)(ws + OFF_W_2) + (size_t)l * DFF * DM, DFF, q / 32, q % 32, scr, lane); continue; } r -= 2 * I_MLP;
.LBB0_39:
	s_andn2_b64 vcc, exec, s[0:1]
	s_cbranch_vccnz .LBB0_41
	s_add_i32 s10, s12, 0xffffac00
	v_readlane_b32 s56, v254, 0
	s_lshr_b32 s2, s10, 12
	v_readlane_b32 s57, v254, 1
	v_readlane_b32 s58, v254, 2
	v_readlane_b32 s59, v254, 3
	v_readlane_b32 s60, v254, 4
	v_readlane_b32 s61, v254, 5
	s_lshl_b64 s[0:1], s[2:3], 26
	v_readlane_b32 s62, v254, 6
	v_readlane_b32 s63, v254, 7
	s_mov_b64 s[56:57], s[60:61]
	s_add_u32 s11, s56, s0
	s_addc_u32 s53, s57, s1
	s_lshl_b64 s[0:1], s[2:3], 25
	s_add_u32 s2, s16, s0
	s_addc_u32 s1, s17, s1
	s_lshl_b32 s0, s10, 1
	s_and_b32 s54, s0, 0x1fc0
	s_lshl_b32 s0, s12, 6
	s_and_b32 s0, s0, 0x7c0
	s_lshl_b32 s10, s0, 2
	s_add_u32 s10, s11, s10
	v_or_b32_e32 v2, s54, v88
	s_addc_u32 s11, s53, 0
	v_mov_b32_e32 v85, v65
	v_lshl_add_u64 v[0:1], s[10:11], 0, v[84:85]
	v_lshlrev_b32_e32 v64, 13, v2
	v_lshl_add_u64 v[60:61], v[0:1], 0, v[64:65]
	v_add_co_u32_e32 v4, vcc, s21, v60
	s_mov_b32 s10, 0x10000
	s_nop 0
	v_addc_co_u32_e32 v5, vcc, 0, v61, vcc
	v_add_co_u32_e32 v8, vcc, s10, v60
	s_mov_b32 s10, 0x28000
	s_nop 0
	v_addc_co_u32_e32 v9, vcc, 0, v61, vcc
	v_add_co_u32_e32 v12, vcc, s23, v60
	global_load_dwordx4 v[0:3], v[60:61], off nt
	s_nop 0
	global_load_dwordx4 v[4:7], v[4:5], off nt
	v_addc_co_u32_e32 v13, vcc, 0, v61, vcc
	v_add_co_u32_e32 v16, vcc, s24, v60
	global_load_dwordx4 v[8:11], v[8:9], off nt
	s_nop 0
	global_load_dwordx4 v[12:15], v[12:13], off nt
	v_addc_co_u32_e32 v17, vcc, 0, v61, vcc
	v_add_co_u32_e32 v20, vcc, s10, v60
	s_mov_b32 s10, 0x38000
	s_nop 0
	v_addc_co_u32_e32 v21, vcc, 0, v61, vcc
	v_add_co_u32_e32 v24, vcc, s25, v60
	global_load_dwordx4 v[16:19], v[16:17], off nt
	s_nop 0
	global_load_dwordx4 v[20:23], v[20:21], off nt
	v_addc_co_u32_e32 v25, vcc, 0, v61, vcc
	v_add_co_u32_e32 v28, vcc, s10, v60
	s_mov_b32 s10, 0x50000
	s_nop 0
	v_addc_co_u32_e32 v29, vcc, 0, v61, vcc
	v_add_co_u32_e32 v32, vcc, s26, v60
	global_load_dwordx4 v[24:27], v[24:25], off nt
	s_nop 0
	global_load_dwordx4 v[28:31], v[28:29], off nt
	v_addc_co_u32_e32 v33, vcc, 0, v61, vcc
	v_add_co_u32_e32 v36, vcc, s27, v60
	v_lshlrev_b32_e32 v64, 1, v66
	s_nop 0
	v_addc_co_u32_e32 v37, vcc, 0, v61, vcc
	v_add_co_u32_e32 v40, vcc, s10, v60
	global_load_dwordx4 v[32:35], v[32:33], off nt
	s_nop 0
	global_load_dwordx4 v[36:39], v[36:37], off nt
	v_addc_co_u32_e32 v41, vcc, 0, v61, vcc
	s_mov_b32 s10, 0x58000
	v_add_co_u32_e32 v44, vcc, s10, v60
	s_mov_b32 s10, 0x68000
	s_nop 0
	v_addc_co_u32_e32 v45, vcc, 0, v61, vcc
	global_load_dwordx4 v[40:43], v[40:41], off nt
	s_nop 0
	global_load_dwordx4 v[44:47], v[44:45], off nt
	v_add_co_u32_e32 v48, vcc, s28, v60
	s_mov_b64 s[58:59], s[62:63]
	s_nop 0
	v_addc_co_u32_e32 v49, vcc, 0, v61, vcc
	global_load_dwordx4 v[48:51], v[48:49], off nt
	v_add_co_u32_e32 v52, vcc, s10, v60
	s_mov_b32 s10, 0x70000
	s_nop 0
	v_addc_co_u32_e32 v53, vcc, 0, v61, vcc
	global_load_dwordx4 v[52:55], v[52:53], off nt
	v_add_co_u32_e32 v56, vcc, s10, v60
	s_lshl_b32 s10, s54, 1
	s_nop 0
	v_addc_co_u32_e32 v57, vcc, 0, v61, vcc
	global_load_dwordx4 v[56:59], v[56:57], off nt
	v_add_co_u32_e32 v60, vcc, s29, v60
	s_add_u32 s10, s2, s10
	s_nop 0
	v_addc_co_u32_e32 v61, vcc, 0, v61, vcc
	global_load_dwordx4 v[60:63], v[60:61], off nt
	s_addc_u32 s11, s1, 0
	s_waitcnt vmcnt(15)
	ds_write2_b32 v89, v0, v1 offset1:1
	ds_write2_b32 v89, v2, v3 offset0:2 offset1:3
	s_waitcnt vmcnt(14)
	ds_write2_b32 v103, v4, v5 offset1:1
	ds_write2_b32 v104, v6, v7 offset1:1
	s_waitcnt vmcnt(13)
	ds_write2_b32 v105, v8, v9 offset1:1
	ds_write2_b32 v106, v10, v11 offset1:1
	s_waitcnt vmcnt(12)
	ds_write2_b32 v107, v12, v13 offset1:1
	ds_write2_b32 v108, v14, v15 offset1:1
	s_waitcnt vmcnt(11)
	ds_write2_b32 v109, v16, v17 offset1:1
	ds_write2_b32 v110, v18, v19 offset1:1
	s_waitcnt vmcnt(10)
	ds_write2_b32 v111, v20, v21 offset1:1
	ds_write2_b32 v112, v22, v23 offset1:1
	s_waitcnt vmcnt(9)
	ds_write2_b32 v113, v24, v25 offset1:1
	ds_write2_b32 v114, v26, v27 offset1:1
	s_waitcnt vmcnt(8)
	ds_write2_b32 v115, v28, v29 offset1:1
	ds_write2_b32 v116, v30, v31 offset1:1
	s_waitcnt vmcnt(7)
	ds_write2_b32 v117, v32, v33 offset1:1
	ds_write2_b32 v118, v34, v35 offset1:1
	v_add_u32_e32 v0, 0x2490, v89
	s_waitcnt vmcnt(6)
	ds_write2_b32 v0, v36, v37 offset1:1
	v_add_u32_e32 v0, 0x2498, v89
	ds_write2_b32 v0, v38, v39 offset1:1
	v_add_u32_e32 v0, 0x28a0, v89
	v_add_u32_e32 v24, 0x400, v91
	v_lshl_add_u64 v[20:21], s[10:11], 0, v[64:65]
	s_waitcnt vmcnt(5)
	ds_write2_b32 v0, v40, v41 offset1:1
	v_add_u32_e32 v0, 0x28a8, v89
	ds_write2_b32 v0, v42, v43 offset1:1
	v_add_u32_e32 v0, 0x2cb0, v89
	s_waitcnt vmcnt(4)
	ds_write2_b32 v0, v44, v45 offset1:1
	v_add_u32_e32 v0, 0x2cb8, v89
	ds_write2_b32 v0, v46, v47 offset1:1
	v_add_u32_e32 v0, 0x30c0, v89
	s_waitcnt vmcnt(3)
; #define LAS __attribute__((address_space(3)))
; __device__ __forceinline__ unsigned cvt_pk_bf16(float lo, float hi) { const bf16x2_t r = __builtin_convertvector((f32x2){lo, hi}, bf16x2_t); return __builtin_bit_cast(unsigned, r); }
; #define LDS_FENCE() asm volatile("s_waitcnt lgkmcnt(0)" ::: "memory")
; __device__ __forceinline__ void transpose_item(const float* src, int ldsrc, bf16_t* dst, int lddst, int kt, int ntile, LAS float* scr, int lane, const float* kscale = nullptr) {
;     ...
;     for (int i = 0; i < 16; ++i) { const int kk = l4 + 4 * i; const f32x4 v = tv[i];
;         LAS float* d = scr + kk * 65 + 4 * l16; d[0] = v[0]; d[1] = v[1]; d[2] = v[2]; d[3] = v[3]; }
;     LDS_FENCE();
;     const int c = lane & 7;
; #pragma unroll
;     for (int j = 0; j < 8; ++j) { const int n = (lane >> 3) + 8 * j; const LAS float* s = scr + (8 * c) * 65 + n;
;         u32x4 o; o.x = cvt_pk_bf16(s[0], s[65]); o.y = cvt_pk_bf16(s[2 * 65], s[3 * 65]); o.z = cvt_pk_bf16(s[4 * 65], s[5 * 65]); o.w = cvt_pk_bf16(s[6 * 65], s[7 * 65]);
;         *(u32x4*)(dst + (size_t)(n0 + n) * lddst + k0 + 8 * c) = o; }
;     LDS_FENCE();
	ds_write2_b32 v0, v48, v49 offset1:1
	v_add_u32_e32 v0, 0x30c8, v89
	ds_write2_b32 v0, v50, v51 offset1:1
	v_add_u32_e32 v0, 0x34d0, v89
	s_waitcnt vmcnt(2)
	ds_write2_b32 v0, v52, v53 offset1:1
	v_add_u32_e32 v0, 0x34d8, v89
	ds_write2_b32 v0, v54, v55 offset1:1
	v_add_u32_e32 v0, 0x38e0, v89
	s_waitcnt vmcnt(1)
	ds_write2_b32 v0, v56, v57 offset1:1
	v_add_u32_e32 v0, 0x38e8, v89
	ds_write2_b32 v0, v58, v59 offset1:1
	v_add_u32_e32 v0, 0x3cf0, v89
	s_waitcnt vmcnt(0)
	ds_write2_b32 v0, v60, v61 offset1:1
	v_add_u32_e32 v0, 0x3cf8, v89
	ds_write2_b32 v0, v62, v63 offset1:1
	s_waitcnt lgkmcnt(0)
	ds_read2_b32 v[4:5], v91 offset0:65 offset1:73
	ds_read2_b32 v[6:7], v91 offset1:8
	ds_read2_b32 v[8:9], v91 offset0:130 offset1:138
	ds_read2_b32 v[10:11], v91 offset0:195 offset1:203
	ds_read2_b32 v[12:13], v24 offset0:4 offset1:12
	ds_read2_b32 v[14:15], v24 offset0:69 offset1:77
	ds_read2_b32 v[16:17], v24 offset0:134 offset1:142
	ds_read2_b32 v[18:19], v24 offset0:199 offset1:207
	s_waitcnt lgkmcnt(6)
	v_cvt_pk_bf16_f32 v0, v6, v4
	v_or_b32_e32 v4, s0, v90
	v_lshlrev_b32_e32 v64, 14, v4
	s_waitcnt lgkmcnt(4)
	v_cvt_pk_bf16_f32 v1, v8, v10
	s_waitcnt lgkmcnt(2)
	v_cvt_pk_bf16_f32 v2, v12, v14
	s_waitcnt lgkmcnt(0)
	v_cvt_pk_bf16_f32 v3, v16, v18
	v_lshl_add_u64 v[22:23], v[20:21], 0, v[64:65]
	global_store_dwordx4 v[22:23], v[0:3], off
	v_or_b32_e32 v4, s0, v92
	v_lshlrev_b32_e32 v64, 14, v4
	v_cvt_pk_bf16_f32 v0, v7, v5
	v_cvt_pk_bf16_f32 v1, v9, v11
	v_cvt_pk_bf16_f32 v2, v13, v15
	v_cvt_pk_bf16_f32 v3, v17, v19
	ds_read2_b32 v[6:7], v91 offset0:81 offset1:89
	ds_read2_b32 v[8:9], v91 offset0:16 offset1:24
	ds_read2_b32 v[10:11], v91 offset0:146 offset1:154
	ds_read2_b32 v[12:13], v91 offset0:211 offset1:219
	ds_read2_b32 v[14:15], v24 offset0:20 offset1:28
	ds_read2_b32 v[16:17], v24 offset0:85 offset1:93
	ds_read2_b32 v[18:19], v24 offset0:150 offset1:158
	ds_read2_b32 v[22:23], v24 offset0:215 offset1:223
	v_lshl_add_u64 v[4:5], v[20:21], 0, v[64:65]
	global_store_dwordx4 v[4:5], v[0:3], off
	v_or_b32_e32 v4, s0, v93
	v_lshlrev_b32_e32 v64, 14, v4
	s_waitcnt lgkmcnt(6)
	v_cvt_pk_bf16_f32 v0, v8, v6
	s_waitcnt lgkmcnt(4)
	v_cvt_pk_bf16_f32 v1, v10, v12
	s_waitcnt lgkmcnt(2)
	v_cvt_pk_bf16_f32 v2, v14, v16
	s_waitcnt lgkmcnt(0)
	v_cvt_pk_bf16_f32 v3, v18, v22
	v_lshl_add_u64 v[4:5], v[20:21], 0, v[64:65]
	global_store_dwordx4 v[4:5], v[0:3], off
	v_or_b32_e32 v4, s0, v94
	v_lshlrev_b32_e32 v64, 14, v4
	v_cvt_pk_bf16_f32 v0, v9, v7
	v_cvt_pk_bf16_f32 v1, v11, v13
	v_cvt_pk_bf16_f32 v2, v15, v17
	v_cvt_pk_bf16_f32 v3, v19, v23
	ds_read2_b32 v[6:7], v91 offset0:32 offset1:40
	ds_read2_b32 v[8:9], v91 offset0:97 offset1:105
	ds_read2_b32 v[10:11], v91 offset0:162 offset1:170
	ds_read2_b32 v[12:13], v91 offset0:227 offset1:235
	ds_read2_b32 v[14:15], v24 offset0:36 offset1:44
	ds_read2_b32 v[16:17], v24 offset0:101 offset1:109
	ds_read2_b32 v[18:19], v24 offset0:166 offset1:174
	ds_read2_b32 v[22:23], v24 offset0:231 offset1:239
	v_lshl_add_u64 v[4:5], v[20:21], 0, v[64:65]
	global_store_dwordx4 v[4:5], v[0:3], off
	v_or_b32_e32 v4, s0, v95
	v_lshlrev_b32_e32 v64, 14, v4
	s_waitcnt lgkmcnt(6)
	v_cvt_pk_bf16_f32 v0, v6, v8
	s_waitcnt lgkmcnt(4)
	v_cvt_pk_bf16_f32 v1, v10, v12
	s_waitcnt lgkmcnt(2)
	v_cvt_pk_bf16_f32 v2, v14, v16
	s_waitcnt lgkmcnt(0)
	v_cvt_pk_bf16_f32 v3, v18, v22
	v_lshl_add_u64 v[4:5], v[20:21], 0, v[64:65]
	global_store_dwordx4 v[4:5], v[0:3], off
	v_or_b32_e32 v4, s0, v96
	v_lshlrev_b32_e32 v64, 14, v4
	v_cvt_pk_bf16_f32 v0, v7, v9
	v_cvt_pk_bf16_f32 v1, v11, v13
	v_cvt_pk_bf16_f32 v2, v15, v17
	v_cvt_pk_bf16_f32 v3, v19, v23
	ds_read2_b32 v[6:7], v91 offset0:48 offset1:56
	ds_read2_b32 v[8:9], v91 offset0:113 offset1:121
	ds_read2_b32 v[10:11], v91 offset0:178 offset1:186
	ds_read2_b32 v[12:13], v91 offset0:243 offset1:251
	ds_read2_b32 v[14:15], v24 offset0:52 offset1:60
	ds_read2_b32 v[16:17], v24 offset0:117 offset1:125
	ds_read2_b32 v[18:19], v24 offset0:182 offset1:190
	ds_read2_b32 v[22:23], v24 offset0:247 offset1:255
	v_lshl_add_u64 v[4:5], v[20:21], 0, v[64:65]
	global_store_dwordx4 v[4:5], v[0:3], off
	v_or_b32_e32 v4, s0, v97
	v_lshlrev_b32_e32 v64, 14, v4
	s_waitcnt lgkmcnt(6)
	v_cvt_pk_bf16_f32 v0, v6, v8
	s_waitcnt lgkmcnt(4)
	v_cvt_pk_bf16_f32 v1, v10, v12
	s_waitcnt lgkmcnt(2)
	v_cvt_pk_bf16_f32 v2, v14, v16
	s_waitcnt lgkmcnt(0)
	v_cvt_pk_bf16_f32 v3, v18, v22
	v_lshl_add_u64 v[4:5], v[20:21], 0, v[64:65]
	global_store_dwordx4 v[4:5], v[0:3], off
	v_or_b32_e32 v4, s0, v98
	v_lshlrev_b32_e32 v64, 14, v4
	v_cvt_pk_bf16_f32 v0, v7, v9
	v_cvt_pk_bf16_f32 v1, v11, v13
	v_cvt_pk_bf16_f32 v2, v15, v17
	v_cvt_pk_bf16_f32 v3, v19, v23
	v_lshl_add_u64 v[4:5], v[20:21], 0, v[64:65]
	global_store_dwordx4 v[4:5], v[0:3], off
	s_waitcnt lgkmcnt(0)

; #define LAS __attribute__((address_space(3)))
; __device__ __forceinline__ void transpose_item(const float* src, int ldsrc, bf16_t* dst, int lddst, int kt, int ntile, LAS float* scr, int lane, const float* kscale = nullptr) {
;     const int k0 = kt * 64, n0 = ntile * 64, l16 = lane & 15, l4 = lane >> 4;
;     f32x4 tv[16];
; #pragma unroll
;     for (int i = 0; i < 16; ++i) tv[i] = *(const f32x4*)(src + (size_t)(k0 + l4 + 4 * i) * ldsrc + n0 + 4 * l16);
;     if (kscale) {
; #pragma unroll
;         for (int i = 0; i < 16; ++i) tv[i] *= kscale[k0 + l4 + 4 * i];
;     }
; #pragma unroll
;     for (int i = 0; i < 16; ++i) { const int kk = l4 + 4 * i; const f32x4 v = tv[i];
;         LAS float* d = scr + kk * 65 + 4 * l16; d[0] = v[0]; d[1] = v[1]; d[2] = v[2]; d[3] = v[3]; }
; __device__ __forceinline__ void phase0(const Params& p, LAS unsigned char* lds, const bool do_gemv = true) {
;     ...
;         if (r < 2 * I_MLP) { const int l = r / I_MLP, q = r % I_MLP; transpose_item(p.mlp_w1 + (size_t)l * DM * DFF, DFF, (bf16_t*)(ws + OFF_W_1) + (size_t)l * DFF * DM, DM, q / 128, q % 128, scr, lane); continue; } r -= 2 * I_MLP;
.LBB0_42:
	s_andn2_b64 vcc, exec, s[0:1]
	s_cbranch_vccnz .LBB0_44
	s_add_i32 s10, s12, 0xffffcc00
	v_readlane_b32 s56, v254, 0
	s_lshr_b32 s2, s10, 12
	v_readlane_b32 s58, v254, 2
	v_readlane_b32 s59, v254, 3
	s_lshl_b64 s[0:1], s[2:3], 26
	s_mov_b64 s[54:55], s[58:59]
	s_add_u32 s11, s54, s0
	s_addc_u32 s53, s55, s1
	s_lshl_b64 s[0:1], s[2:3], 25
	s_add_u32 s2, s18, s0
	s_addc_u32 s1, s19, s1
	s_lshr_b32 s0, s10, 1
	s_and_b32 s54, s0, 0x7c0
	s_lshl_b32 s0, s12, 6
	s_and_b32 s0, s0, 0x1fc0
	s_lshl_b32 s10, s0, 2
	s_add_u32 s10, s11, s10
	v_or_b32_e32 v2, s54, v88
	s_addc_u32 s11, s53, 0
	v_mov_b32_e32 v85, v65
	v_lshl_add_u64 v[0:1], s[10:11], 0, v[84:85]
	v_lshlrev_b32_e32 v64, 15, v2
	v_lshl_add_u64 v[60:61], v[0:1], 0, v[64:65]
	v_add_co_u32_e32 v4, vcc, s24, v60
	s_mov_b32 s10, 0x80000
	s_nop 0
	v_addc_co_u32_e32 v5, vcc, 0, v61, vcc
	v_add_co_u32_e32 v8, vcc, s26, v60
	global_load_dwordx4 v[0:3], v[60:61], off nt
	s_nop 0
	global_load_dwordx4 v[4:7], v[4:5], off nt
	v_addc_co_u32_e32 v9, vcc, 0, v61, vcc
	v_add_co_u32_e32 v12, vcc, s28, v60
	v_lshlrev_b32_e32 v64, 1, v66
	s_nop 0
	v_addc_co_u32_e32 v13, vcc, 0, v61, vcc
	v_add_co_u32_e32 v16, vcc, s10, v60
	s_mov_b32 s10, 0xa0000
	s_nop 0
	v_addc_co_u32_e32 v17, vcc, 0, v61, vcc
	v_add_co_u32_e32 v20, vcc, s10, v60
	s_mov_b32 s10, 0xe0000
	s_nop 0
	v_addc_co_u32_e32 v21, vcc, 0, v61, vcc
	v_add_co_u32_e32 v24, vcc, s30, v60
	global_load_dwordx4 v[8:11], v[8:9], off nt
	s_nop 0
	global_load_dwordx4 v[12:15], v[12:13], off nt
	v_addc_co_u32_e32 v25, vcc, 0, v61, vcc
	v_add_co_u32_e32 v28, vcc, s10, v60
	s_mov_b32 s10, 0x100000
	s_nop 0
	v_addc_co_u32_e32 v29, vcc, 0, v61, vcc
	v_add_co_u32_e32 v32, vcc, s10, v60
	s_mov_b32 s10, 0x140000
	s_nop 0
	v_addc_co_u32_e32 v33, vcc, 0, v61, vcc
	v_add_co_u32_e32 v36, vcc, s31, v60
	global_load_dwordx4 v[16:19], v[16:17], off nt
	s_nop 0
	global_load_dwordx4 v[20:23], v[20:21], off nt
	v_addc_co_u32_e32 v37, vcc, 0, v61, vcc
	global_load_dwordx4 v[24:27], v[24:25], off nt
	s_nop 0
	global_load_dwordx4 v[28:31], v[28:29], off nt
	v_add_co_u32_e32 v40, vcc, s10, v60
	global_load_dwordx4 v[32:35], v[32:33], off nt
	s_nop 0
	global_load_dwordx4 v[36:39], v[36:37], off nt
	v_addc_co_u32_e32 v41, vcc, 0, v61, vcc
	s_mov_b32 s10, 0x160000
	v_add_co_u32_e32 v44, vcc, s10, v60
	s_mov_b32 s10, 0x180000
	s_nop 0
	v_addc_co_u32_e32 v45, vcc, 0, v61, vcc
	global_load_dwordx4 v[40:43], v[40:41], off nt
	s_nop 0
	global_load_dwordx4 v[44:47], v[44:45], off nt
	v_add_co_u32_e32 v48, vcc, s10, v60
	s_mov_b32 s10, 0x1a0000
	s_nop 0
	v_addc_co_u32_e32 v49, vcc, 0, v61, vcc
	global_load_dwordx4 v[48:51], v[48:49], off nt
	v_add_co_u32_e32 v52, vcc, s10, v60
	s_mov_b32 s10, 0x1c0000
	s_nop 0
	v_addc_co_u32_e32 v53, vcc, 0, v61, vcc
	global_load_dwordx4 v[52:55], v[52:53], off nt
	v_add_co_u32_e32 v56, vcc, s10, v60
	s_mov_b32 s10, 0x1e0000
	s_nop 0
	v_addc_co_u32_e32 v57, vcc, 0, v61, vcc
	global_load_dwordx4 v[56:59], v[56:57], off nt
	v_add_co_u32_e32 v60, vcc, s10, v60
	s_lshl_b32 s10, s54, 1
	s_nop 0
	v_addc_co_u32_e32 v61, vcc, 0, v61, vcc
	global_load_dwordx4 v[60:63], v[60:61], off nt
	s_add_u32 s10, s2, s10
	s_addc_u32 s11, s1, 0
	v_readlane_b32 s57, v254, 1
	v_readlane_b32 s60, v254, 4
	v_readlane_b32 s61, v254, 5
	s_waitcnt vmcnt(15)
	ds_write2_b32 v89, v0, v1 offset1:1
	ds_write2_b32 v89, v2, v3 offset0:2 offset1:3
	s_waitcnt vmcnt(14)
	ds_write2_b32 v103, v4, v5 offset1:1
	ds_write2_b32 v104, v6, v7 offset1:1
	s_waitcnt vmcnt(13)
	ds_write2_b32 v105, v8, v9 offset1:1
	ds_write2_b32 v106, v10, v11 offset1:1
	s_waitcnt vmcnt(12)
	ds_write2_b32 v107, v12, v13 offset1:1
	ds_write2_b32 v108, v14, v15 offset1:1
	s_waitcnt vmcnt(11)
	ds_write2_b32 v109, v16, v17 offset1:1
	ds_write2_b32 v110, v18, v19 offset1:1
	s_waitcnt vmcnt(10)
	ds_write2_b32 v111, v20, v21 offset1:1
	ds_write2_b32 v112, v22, v23 offset1:1
	s_waitcnt vmcnt(9)
	ds_write2_b32 v113, v24, v25 offset1:1
	ds_write2_b32 v114, v26, v27 offset1:1
	s_waitcnt vmcnt(8)
	ds_write2_b32 v115, v28, v29 offset1:1
	ds_write2_b32 v116, v30, v31 offset1:1
	s_waitcnt vmcnt(7)
	ds_write2_b32 v117, v32, v33 offset1:1
	ds_write2_b32 v118, v34, v35 offset1:1
	v_add_u32_e32 v0, 0x2490, v89
	s_waitcnt vmcnt(6)
	ds_write2_b32 v0, v36, v37 offset1:1
	v_add_u32_e32 v0, 0x2498, v89
	ds_write2_b32 v0, v38, v39 offset1:1
	v_add_u32_e32 v0, 0x28a0, v89
	v_add_u32_e32 v24, 0x400, v91
	v_lshl_add_u64 v[20:21], s[10:11], 0, v[64:65]
	v_readlane_b32 s62, v254, 6
	s_waitcnt vmcnt(5)
	ds_write2_b32 v0, v40, v41 offset1:1
	v_add_u32_e32 v0, 0x28a8, v89
	ds_write2_b32 v0, v42, v43 offset1:1
	v_add_u32_e32 v0, 0x2cb0, v89
	s_waitcnt vmcnt(4)
	ds_write2_b32 v0, v44, v45 offset1:1
	v_add_u32_e32 v0, 0x2cb8, v89
	ds_write2_b32 v0, v46, v47 offset1:1
	v_add_u32_e32 v0, 0x30c0, v89
	s_waitcnt vmcnt(3)
; #define LAS __attribute__((address_space(3)))
; __device__ __forceinline__ unsigned cvt_pk_bf16(float lo, float hi) { const bf16x2_t r = __builtin_convertvector((f32x2){lo, hi}, bf16x2_t); return __builtin_bit_cast(unsigned, r); }
; #define LDS_FENCE() asm volatile("s_waitcnt lgkmcnt(0)" ::: "memory")
; __device__ __forceinline__ void transpose_item(const float* src, int ldsrc, bf16_t* dst, int lddst, int kt, int ntile, LAS float* scr, int lane, const float* kscale = nullptr) {
;     ...
;     for (int i = 0; i < 16; ++i) { const int kk = l4 + 4 * i; const f32x4 v = tv[i];
;         LAS float* d = scr + kk * 65 + 4 * l16; d[0] = v[0]; d[1] = v[1]; d[2] = v[2]; d[3] = v[3]; }
;     LDS_FENCE();
;     const int c = lane & 7;
; #pragma unroll
;     for (int j = 0; j < 8; ++j) { const int n = (lane >> 3) + 8 * j; const LAS float* s = scr + (8 * c) * 65 + n;
;         u32x4 o; o.x = cvt_pk_bf16(s[0], s[65]); o.y = cvt_pk_bf16(s[2 * 65], s[3 * 65]); o.z = cvt_pk_bf16(s[4 * 65], s[5 * 65]); o.w = cvt_pk_bf16(s[6 * 65], s[7 * 65]);
;         *(u32x4*)(dst + (size_t)(n0 + n) * lddst + k0 + 8 * c) = o; }
;     LDS_FENCE();
	ds_write2_b32 v0, v48, v49 offset1:1
	v_add_u32_e32 v0, 0x30c8, v89
	ds_write2_b32 v0, v50, v51 offset1:1
	v_add_u32_e32 v0, 0x34d0, v89
	v_readlane_b32 s63, v254, 7
	s_waitcnt vmcnt(2)
	ds_write2_b32 v0, v52, v53 offset1:1
	v_add_u32_e32 v0, 0x34d8, v89
	ds_write2_b32 v0, v54, v55 offset1:1
	v_add_u32_e32 v0, 0x38e0, v89
	s_waitcnt vmcnt(1)
	ds_write2_b32 v0, v56, v57 offset1:1
	v_add_u32_e32 v0, 0x38e8, v89
	ds_write2_b32 v0, v58, v59 offset1:1
	v_add_u32_e32 v0, 0x3cf0, v89
	s_waitcnt vmcnt(0)
	ds_write2_b32 v0, v60, v61 offset1:1
	v_add_u32_e32 v0, 0x3cf8, v89
	ds_write2_b32 v0, v62, v63 offset1:1
	s_waitcnt lgkmcnt(0)
	ds_read2_b32 v[4:5], v91 offset0:65 offset1:73
	ds_read2_b32 v[6:7], v91 offset1:8
	ds_read2_b32 v[8:9], v91 offset0:130 offset1:138
	ds_read2_b32 v[10:11], v91 offset0:195 offset1:203
	ds_read2_b32 v[12:13], v24 offset0:4 offset1:12
	ds_read2_b32 v[14:15], v24 offset0:69 offset1:77
	ds_read2_b32 v[16:17], v24 offset0:134 offset1:142
	ds_read2_b32 v[18:19], v24 offset0:199 offset1:207
	s_waitcnt lgkmcnt(6)
	v_cvt_pk_bf16_f32 v0, v6, v4
	v_or_b32_e32 v4, s0, v90
	v_lshlrev_b32_e32 v64, 12, v4
	s_waitcnt lgkmcnt(4)
	v_cvt_pk_bf16_f32 v1, v8, v10
	s_waitcnt lgkmcnt(2)
	v_cvt_pk_bf16_f32 v2, v12, v14
	s_waitcnt lgkmcnt(0)
	v_cvt_pk_bf16_f32 v3, v16, v18
	v_lshl_add_u64 v[22:23], v[20:21], 0, v[64:65]
	global_store_dwordx4 v[22:23], v[0:3], off
	v_or_b32_e32 v4, s0, v92
	v_lshlrev_b32_e32 v64, 12, v4
	v_cvt_pk_bf16_f32 v0, v7, v5
	v_cvt_pk_bf16_f32 v1, v9, v11
	v_cvt_pk_bf16_f32 v2, v13, v15
	v_cvt_pk_bf16_f32 v3, v17, v19
	ds_read2_b32 v[6:7], v91 offset0:81 offset1:89
	ds_read2_b32 v[8:9], v91 offset0:16 offset1:24
	ds_read2_b32 v[10:11], v91 offset0:146 offset1:154
	ds_read2_b32 v[12:13], v91 offset0:211 offset1:219
	ds_read2_b32 v[14:15], v24 offset0:20 offset1:28
	ds_read2_b32 v[16:17], v24 offset0:85 offset1:93
	ds_read2_b32 v[18:19], v24 offset0:150 offset1:158
	ds_read2_b32 v[22:23], v24 offset0:215 offset1:223
	v_lshl_add_u64 v[4:5], v[20:21], 0, v[64:65]
	global_store_dwordx4 v[4:5], v[0:3], off
	v_or_b32_e32 v4, s0, v93
	v_lshlrev_b32_e32 v64, 12, v4
	s_waitcnt lgkmcnt(6)
	v_cvt_pk_bf16_f32 v0, v8, v6
	s_waitcnt lgkmcnt(4)
	v_cvt_pk_bf16_f32 v1, v10, v12
	s_waitcnt lgkmcnt(2)
	v_cvt_pk_bf16_f32 v2, v14, v16
	s_waitcnt lgkmcnt(0)
	v_cvt_pk_bf16_f32 v3, v18, v22
	v_lshl_add_u64 v[4:5], v[20:21], 0, v[64:65]
	global_store_dwordx4 v[4:5], v[0:3], off
	v_or_b32_e32 v4, s0, v94
	v_lshlrev_b32_e32 v64, 12, v4
	v_cvt_pk_bf16_f32 v0, v9, v7
	v_cvt_pk_bf16_f32 v1, v11, v13
	v_cvt_pk_bf16_f32 v2, v15, v17
	v_cvt_pk_bf16_f32 v3, v19, v23
	ds_read2_b32 v[6:7], v91 offset0:32 offset1:40
	ds_read2_b32 v[8:9], v91 offset0:97 offset1:105
	ds_read2_b32 v[10:11], v91 offset0:162 offset1:170
	ds_read2_b32 v[12:13], v91 offset0:227 offset1:235
	ds_read2_b32 v[14:15], v24 offset0:36 offset1:44
	ds_read2_b32 v[16:17], v24 offset0:101 offset1:109
	ds_read2_b32 v[18:19], v24 offset0:166 offset1:174
	ds_read2_b32 v[22:23], v24 offset0:231 offset1:239
	v_lshl_add_u64 v[4:5], v[20:21], 0, v[64:65]
	global_store_dwordx4 v[4:5], v[0:3], off
	v_or_b32_e32 v4, s0, v95
	v_lshlrev_b32_e32 v64, 12, v4
	s_waitcnt lgkmcnt(6)
	v_cvt_pk_bf16_f32 v0, v6, v8
	s_waitcnt lgkmcnt(4)
	v_cvt_pk_bf16_f32 v1, v10, v12
	s_waitcnt lgkmcnt(2)
	v_cvt_pk_bf16_f32 v2, v14, v16
	s_waitcnt lgkmcnt(0)
	v_cvt_pk_bf16_f32 v3, v18, v22
	v_lshl_add_u64 v[4:5], v[20:21], 0, v[64:65]
	global_store_dwordx4 v[4:5], v[0:3], off
	v_or_b32_e32 v4, s0, v96
	v_lshlrev_b32_e32 v64, 12, v4
	v_cvt_pk_bf16_f32 v0, v7, v9
	v_cvt_pk_bf16_f32 v1, v11, v13
	v_cvt_pk_bf16_f32 v2, v15, v17
	v_cvt_pk_bf16_f32 v3, v19, v23
	ds_read2_b32 v[6:7], v91 offset0:48 offset1:56
	ds_read2_b32 v[8:9], v91 offset0:113 offset1:121
	ds_read2_b32 v[10:11], v91 offset0:178 offset1:186
	ds_read2_b32 v[12:13], v91 offset0:243 offset1:251
	ds_read2_b32 v[14:15], v24 offset0:52 offset1:60
	ds_read2_b32 v[16:17], v24 offset0:117 offset1:125
	ds_read2_b32 v[18:19], v24 offset0:182 offset1:190
	ds_read2_b32 v[22:23], v24 offset0:247 offset1:255
	v_lshl_add_u64 v[4:5], v[20:21], 0, v[64:65]
	global_store_dwordx4 v[4:5], v[0:3], off
	v_or_b32_e32 v4, s0, v97
	v_lshlrev_b32_e32 v64, 12, v4
	s_waitcnt lgkmcnt(6)
	v_cvt_pk_bf16_f32 v0, v6, v8
	s_waitcnt lgkmcnt(4)
	v_cvt_pk_bf16_f32 v1, v10, v12
	s_waitcnt lgkmcnt(2)
	v_cvt_pk_bf16_f32 v2, v14, v16
	s_waitcnt lgkmcnt(0)
	v_cvt_pk_bf16_f32 v3, v18, v22
	v_lshl_add_u64 v[4:5], v[20:21], 0, v[64:65]
	global_store_dwordx4 v[4:5], v[0:3], off
	v_or_b32_e32 v4, s0, v98
	v_lshlrev_b32_e32 v64, 12, v4
	v_cvt_pk_bf16_f32 v0, v7, v9
	v_cvt_pk_bf16_f32 v1, v11, v13
	v_cvt_pk_bf16_f32 v2, v15, v17
	v_cvt_pk_bf16_f32 v3, v19, v23
	v_lshl_add_u64 v[4:5], v[20:21], 0, v[64:65]
	global_store_dwordx4 v[4:5], v[0:3], off
	s_waitcnt lgkmcnt(0)

; #define LAS __attribute__((address_space(3)))
; __device__ __forceinline__ void transpose_item(const float* src, int ldsrc, bf16_t* dst, int lddst, int kt, int ntile, LAS float* scr, int lane, const float* kscale = nullptr) {
;     const int k0 = kt * 64, n0 = ntile * 64, l16 = lane & 15, l4 = lane >> 4;
;     f32x4 tv[16];
; #pragma unroll
;     for (int i = 0; i < 16; ++i) tv[i] = *(const f32x4*)(src + (size_t)(k0 + l4 + 4 * i) * ldsrc + n0 + 4 * l16);
;     if (kscale) {
; #pragma unroll
;         for (int i = 0; i < 16; ++i) tv[i] *= kscale[k0 + l4 + 4 * i];
;     }
; #pragma unroll
;     for (int i = 0; i < 16; ++i) { const int kk = l4 + 4 * i; const f32x4 v = tv[i];
;         LAS float* d = scr + kk * 65 + 4 * l16; d[0] = v[0]; d[1] = v[1]; d[2] = v[2]; d[3] = v[3]; }
; __device__ __forceinline__ void phase0(const Params& p, LAS unsigned char* lds, const bool do_gemv = true) {
;     ...
;         if (r < I_BIN) { transpose_item(p.b_w_in, 4096, (bf16_t*)(ws + OFF_W_BIN), 2048, r / 64, r % 64, scr, lane); continue; } r -= I_BIN;
.LBB0_45:
	s_andn2_b64 vcc, exec, s[0:1]
	s_cbranch_vccnz .LBB0_47
	s_and_b32 s0, s12, 0x3fc0
	s_lshl_b32 s1, s12, 6
	s_addk_i32 s0, 0xd400
	s_and_b32 s10, s1, 0xfc0
	v_or_b32_e32 v2, s0, v88
	s_lshl_b32 s2, s10, 2
	v_lshl_add_u64 v[0:1], v[76:77], 0, s[2:3]
	v_lshlrev_b32_e32 v64, 12, v2
	v_lshl_add_u64 v[60:61], v[64:65], 2, v[0:1]
	v_add_co_u32_e32 v4, vcc, 0x10000, v60
	s_mov_b32 s1, s3
	s_nop 0
	v_addc_co_u32_e32 v5, vcc, 0, v61, vcc
	v_add_co_u32_e32 v8, vcc, 0x20000, v60
	global_load_dwordx4 v[0:3], v[60:61], off nt
	s_nop 0
	global_load_dwordx4 v[4:7], v[4:5], off nt
	v_addc_co_u32_e32 v9, vcc, 0, v61, vcc
	v_add_co_u32_e32 v12, vcc, 0x30000, v60
	s_nop 1
	v_addc_co_u32_e32 v13, vcc, 0, v61, vcc
	v_add_co_u32_e32 v16, vcc, 0x40000, v60
	global_load_dwordx4 v[8:11], v[8:9], off nt
	s_nop 0
	global_load_dwordx4 v[12:15], v[12:13], off nt
	v_addc_co_u32_e32 v17, vcc, 0, v61, vcc
	v_add_co_u32_e32 v20, vcc, 0x50000, v60
	s_nop 1
	v_addc_co_u32_e32 v21, vcc, 0, v61, vcc
	v_add_co_u32_e32 v24, vcc, 0x60000, v60
	global_load_dwordx4 v[16:19], v[16:17], off nt
	s_nop 0
	global_load_dwordx4 v[20:23], v[20:21], off nt
	v_addc_co_u32_e32 v25, vcc, 0, v61, vcc
	v_add_co_u32_e32 v28, vcc, 0x70000, v60
	s_nop 1
	v_addc_co_u32_e32 v29, vcc, 0, v61, vcc
	v_add_co_u32_e32 v32, vcc, 0x80000, v60
	global_load_dwordx4 v[24:27], v[24:25], off nt
	s_nop 0
	global_load_dwordx4 v[28:31], v[28:29], off nt
	v_addc_co_u32_e32 v33, vcc, 0, v61, vcc
	v_add_co_u32_e32 v36, vcc, 0x90000, v60
	s_nop 1
	v_addc_co_u32_e32 v37, vcc, 0, v61, vcc
	v_add_co_u32_e32 v40, vcc, 0xa0000, v60
	global_load_dwordx4 v[32:35], v[32:33], off nt
	s_nop 0
	global_load_dwordx4 v[36:39], v[36:37], off nt
	v_addc_co_u32_e32 v41, vcc, 0, v61, vcc
	v_add_co_u32_e32 v44, vcc, 0xb0000, v60
	s_nop 1
	v_addc_co_u32_e32 v45, vcc, 0, v61, vcc
	global_load_dwordx4 v[40:43], v[40:41], off nt
	s_nop 0
	global_load_dwordx4 v[44:47], v[44:45], off nt
	v_add_co_u32_e32 v48, vcc, 0xc0000, v60
	s_nop 1
	v_addc_co_u32_e32 v49, vcc, 0, v61, vcc
	v_add_co_u32_e32 v52, vcc, 0xd0000, v60
	s_nop 1
	v_addc_co_u32_e32 v53, vcc, 0, v61, vcc
	global_load_dwordx4 v[48:51], v[48:49], off nt
	s_nop 0
	global_load_dwordx4 v[52:55], v[52:53], off nt
	v_add_co_u32_e32 v56, vcc, 0xe0000, v60
	s_nop 1
	v_addc_co_u32_e32 v57, vcc, 0, v61, vcc
	global_load_dwordx4 v[56:59], v[56:57], off nt
	v_add_co_u32_e32 v60, vcc, 0xf0000, v60
	s_nop 1
	v_addc_co_u32_e32 v61, vcc, 0, v61, vcc
	global_load_dwordx4 v[60:63], v[60:61], off nt
	s_waitcnt vmcnt(15)
	ds_write2_b32 v89, v0, v1 offset1:1
	ds_write2_b32 v89, v2, v3 offset0:2 offset1:3
	s_waitcnt vmcnt(14)
	ds_write2_b32 v103, v4, v5 offset1:1
	ds_write2_b32 v104, v6, v7 offset1:1
	s_waitcnt vmcnt(13)
	ds_write2_b32 v105, v8, v9 offset1:1
	ds_write2_b32 v106, v10, v11 offset1:1
	s_waitcnt vmcnt(12)
	ds_write2_b32 v107, v12, v13 offset1:1
	ds_write2_b32 v108, v14, v15 offset1:1
	s_waitcnt vmcnt(11)
	ds_write2_b32 v109, v16, v17 offset1:1
	ds_write2_b32 v110, v18, v19 offset1:1
	s_waitcnt vmcnt(10)
	ds_write2_b32 v111, v20, v21 offset1:1
	ds_write2_b32 v112, v22, v23 offset1:1
	s_waitcnt vmcnt(9)
	ds_write2_b32 v113, v24, v25 offset1:1
	ds_write2_b32 v114, v26, v27 offset1:1
	s_waitcnt vmcnt(8)
	ds_write2_b32 v115, v28, v29 offset1:1
	ds_write2_b32 v116, v30, v31 offset1:1
	s_waitcnt vmcnt(7)
	ds_write2_b32 v117, v32, v33 offset1:1
	ds_write2_b32 v118, v34, v35 offset1:1
	v_add_u32_e32 v0, 0x2490, v89
	s_waitcnt vmcnt(6)
	ds_write2_b32 v0, v36, v37 offset1:1
	v_add_u32_e32 v0, 0x2498, v89
	ds_write2_b32 v0, v38, v39 offset1:1
	v_add_u32_e32 v0, 0x28a0, v89
	v_add_u32_e32 v24, 0x400, v91
	v_lshl_add_u64 v[20:21], s[0:1], 1, v[68:69]
	s_waitcnt vmcnt(5)
	ds_write2_b32 v0, v40, v41 offset1:1
	v_add_u32_e32 v0, 0x28a8, v89
	ds_write2_b32 v0, v42, v43 offset1:1
	v_add_u32_e32 v0, 0x2cb0, v89
	s_waitcnt vmcnt(4)
	ds_write2_b32 v0, v44, v45 offset1:1
	v_add_u32_e32 v0, 0x2cb8, v89
	ds_write2_b32 v0, v46, v47 offset1:1
	v_add_u32_e32 v0, 0x30c0, v89
	s_waitcnt vmcnt(3)
	ds_write2_b32 v0, v48, v49 offset1:1
	v_add_u32_e32 v0, 0x30c8, v89
	ds_write2_b32 v0, v50, v51 offset1:1
	v_add_u32_e32 v0, 0x34d0, v89
	s_waitcnt vmcnt(2)
	ds_write2_b32 v0, v52, v53 offset1:1
	v_add_u32_e32 v0, 0x34d8, v89
	ds_write2_b32 v0, v54, v55 offset1:1
	v_add_u32_e32 v0, 0x38e0, v89
	s_waitcnt vmcnt(1)
; #define LAS __attribute__((address_space(3)))
; __device__ __forceinline__ unsigned cvt_pk_bf16(float lo, float hi) { const bf16x2_t r = __builtin_convertvector((f32x2){lo, hi}, bf16x2_t); return __builtin_bit_cast(unsigned, r); }
; #define LDS_FENCE() asm volatile("s_waitcnt lgkmcnt(0)" ::: "memory")
; __device__ __forceinline__ void transpose_item(const float* src, int ldsrc, bf16_t* dst, int lddst, int kt, int ntile, LAS float* scr, int lane, const float* kscale = nullptr) {
;     ...
;     LDS_FENCE();
;     const int c = lane & 7;
; #pragma unroll
;     for (int j = 0; j < 8; ++j) { const int n = (lane >> 3) + 8 * j; const LAS float* s = scr + (8 * c) * 65 + n;
;         u32x4 o; o.x = cvt_pk_bf16(s[0], s[65]); o.y = cvt_pk_bf16(s[2 * 65], s[3 * 65]); o.z = cvt_pk_bf16(s[4 * 65], s[5 * 65]); o.w = cvt_pk_bf16(s[6 * 65], s[7 * 65]);
;         *(u32x4*)(dst + (size_t)(n0 + n) * lddst + k0 + 8 * c) = o; }
;     LDS_FENCE();
	ds_write2_b32 v0, v56, v57 offset1:1
	v_add_u32_e32 v0, 0x38e8, v89
	ds_write2_b32 v0, v58, v59 offset1:1
	v_add_u32_e32 v0, 0x3cf0, v89
	s_waitcnt vmcnt(0)
	ds_write2_b32 v0, v60, v61 offset1:1
	v_add_u32_e32 v0, 0x3cf8, v89
	ds_write2_b32 v0, v62, v63 offset1:1
	s_waitcnt lgkmcnt(0)
	ds_read2_b32 v[4:5], v91 offset0:65 offset1:73
	ds_read2_b32 v[6:7], v91 offset1:8
	ds_read2_b32 v[8:9], v91 offset0:130 offset1:138
	ds_read2_b32 v[10:11], v91 offset0:195 offset1:203
	ds_read2_b32 v[12:13], v24 offset0:4 offset1:12
	ds_read2_b32 v[14:15], v24 offset0:69 offset1:77
	ds_read2_b32 v[16:17], v24 offset0:134 offset1:142
	ds_read2_b32 v[18:19], v24 offset0:199 offset1:207
	s_waitcnt lgkmcnt(6)
	v_cvt_pk_bf16_f32 v0, v6, v4
	v_or_b32_e32 v4, s10, v90
	v_lshlrev_b32_e32 v64, 12, v4
	s_waitcnt lgkmcnt(4)
	v_cvt_pk_bf16_f32 v1, v8, v10
	s_waitcnt lgkmcnt(2)
	v_cvt_pk_bf16_f32 v2, v12, v14
	s_waitcnt lgkmcnt(0)
	v_cvt_pk_bf16_f32 v3, v16, v18
	v_lshl_add_u64 v[22:23], v[20:21], 0, v[64:65]
	global_store_dwordx4 v[22:23], v[0:3], off
	v_or_b32_e32 v4, s10, v92
	v_lshlrev_b32_e32 v64, 12, v4
	v_cvt_pk_bf16_f32 v0, v7, v5
	v_cvt_pk_bf16_f32 v1, v9, v11
	v_cvt_pk_bf16_f32 v2, v13, v15
	v_cvt_pk_bf16_f32 v3, v17, v19
	ds_read2_b32 v[6:7], v91 offset0:81 offset1:89
	ds_read2_b32 v[8:9], v91 offset0:16 offset1:24
	ds_read2_b32 v[10:11], v91 offset0:146 offset1:154
	ds_read2_b32 v[12:13], v91 offset0:211 offset1:219
	ds_read2_b32 v[14:15], v24 offset0:20 offset1:28
	ds_read2_b32 v[16:17], v24 offset0:85 offset1:93
	ds_read2_b32 v[18:19], v24 offset0:150 offset1:158
	ds_read2_b32 v[22:23], v24 offset0:215 offset1:223
	v_lshl_add_u64 v[4:5], v[20:21], 0, v[64:65]
	global_store_dwordx4 v[4:5], v[0:3], off
	v_or_b32_e32 v4, s10, v93
	v_lshlrev_b32_e32 v64, 12, v4
	s_waitcnt lgkmcnt(6)
	v_cvt_pk_bf16_f32 v0, v8, v6
	s_waitcnt lgkmcnt(4)
	v_cvt_pk_bf16_f32 v1, v10, v12
	s_waitcnt lgkmcnt(2)
	v_cvt_pk_bf16_f32 v2, v14, v16
	s_waitcnt lgkmcnt(0)
	v_cvt_pk_bf16_f32 v3, v18, v22
	v_lshl_add_u64 v[4:5], v[20:21], 0, v[64:65]
	global_store_dwordx4 v[4:5], v[0:3], off
	v_or_b32_e32 v4, s10, v94
	v_lshlrev_b32_e32 v64, 12, v4
	v_cvt_pk_bf16_f32 v0, v9, v7
	v_cvt_pk_bf16_f32 v1, v11, v13
	v_cvt_pk_bf16_f32 v2, v15, v17
	v_cvt_pk_bf16_f32 v3, v19, v23
	ds_read2_b32 v[6:7], v91 offset0:32 offset1:40
	ds_read2_b32 v[8:9], v91 offset0:97 offset1:105
	ds_read2_b32 v[10:11], v91 offset0:162 offset1:170
	ds_read2_b32 v[12:13], v91 offset0:227 offset1:235
	ds_read2_b32 v[14:15], v24 offset0:36 offset1:44
	ds_read2_b32 v[16:17], v24 offset0:101 offset1:109
	ds_read2_b32 v[18:19], v24 offset0:166 offset1:174
	ds_read2_b32 v[22:23], v24 offset0:231 offset1:239
	v_lshl_add_u64 v[4:5], v[20:21], 0, v[64:65]
	global_store_dwordx4 v[4:5], v[0:3], off
	v_or_b32_e32 v4, s10, v95
	v_lshlrev_b32_e32 v64, 12, v4
	s_waitcnt lgkmcnt(6)
	v_cvt_pk_bf16_f32 v0, v6, v8
	s_waitcnt lgkmcnt(4)
	v_cvt_pk_bf16_f32 v1, v10, v12
	s_waitcnt lgkmcnt(2)
	v_cvt_pk_bf16_f32 v2, v14, v16
	s_waitcnt lgkmcnt(0)
	v_cvt_pk_bf16_f32 v3, v18, v22
	v_lshl_add_u64 v[4:5], v[20:21], 0, v[64:65]
	global_store_dwordx4 v[4:5], v[0:3], off
	v_or_b32_e32 v4, s10, v96
	v_lshlrev_b32_e32 v64, 12, v4
	v_cvt_pk_bf16_f32 v0, v7, v9
	v_cvt_pk_bf16_f32 v1, v11, v13
	v_cvt_pk_bf16_f32 v2, v15, v17
	v_cvt_pk_bf16_f32 v3, v19, v23
	ds_read2_b32 v[6:7], v91 offset0:48 offset1:56
	ds_read2_b32 v[8:9], v91 offset0:113 offset1:121
	ds_read2_b32 v[10:11], v91 offset0:178 offset1:186
	ds_read2_b32 v[12:13], v91 offset0:243 offset1:251
	ds_read2_b32 v[14:15], v24 offset0:52 offset1:60
	ds_read2_b32 v[16:17], v24 offset0:117 offset1:125
	ds_read2_b32 v[18:19], v24 offset0:182 offset1:190
	ds_read2_b32 v[22:23], v24 offset0:247 offset1:255
	v_lshl_add_u64 v[4:5], v[20:21], 0, v[64:65]
	global_store_dwordx4 v[4:5], v[0:3], off
	v_or_b32_e32 v4, s10, v97
	v_lshlrev_b32_e32 v64, 12, v4
	s_waitcnt lgkmcnt(6)
	v_cvt_pk_bf16_f32 v0, v6, v8
	s_waitcnt lgkmcnt(4)
	v_cvt_pk_bf16_f32 v1, v10, v12
	s_waitcnt lgkmcnt(2)
	v_cvt_pk_bf16_f32 v2, v14, v16
	s_waitcnt lgkmcnt(0)
	v_cvt_pk_bf16_f32 v3, v18, v22
	v_lshl_add_u64 v[4:5], v[20:21], 0, v[64:65]
	global_store_dwordx4 v[4:5], v[0:3], off
	v_or_b32_e32 v4, s10, v98
	v_lshlrev_b32_e32 v64, 12, v4
	v_cvt_pk_bf16_f32 v0, v7, v9
	v_cvt_pk_bf16_f32 v1, v11, v13
	v_cvt_pk_bf16_f32 v2, v15, v17
	v_cvt_pk_bf16_f32 v3, v19, v23
	v_lshl_add_u64 v[4:5], v[20:21], 0, v[64:65]
	global_store_dwordx4 v[4:5], v[0:3], off
	s_waitcnt lgkmcnt(0)

; #define LAS __attribute__((address_space(3)))
; __device__ __forceinline__ void transpose_item(const float* src, int ldsrc, bf16_t* dst, int lddst, int kt, int ntile, LAS float* scr, int lane, const float* kscale = nullptr) {
;     const int k0 = kt * 64, n0 = ntile * 64, l16 = lane & 15, l4 = lane >> 4;
;     f32x4 tv[16];
; #pragma unroll
;     for (int i = 0; i < 16; ++i) tv[i] = *(const f32x4*)(src + (size_t)(k0 + l4 + 4 * i) * ldsrc + n0 + 4 * l16);
;     if (kscale) {
; #pragma unroll
;         for (int i = 0; i < 16; ++i) tv[i] *= kscale[k0 + l4 + 4 * i];
;     }
; #pragma unroll
;     for (int i = 0; i < 16; ++i) { const int kk = l4 + 4 * i; const f32x4 v = tv[i];
;         LAS float* d = scr + kk * 65 + 4 * l16; d[0] = v[0]; d[1] = v[1]; d[2] = v[2]; d[3] = v[3]; }
; __device__ __forceinline__ void phase0(const Params& p, LAS unsigned char* lds, const bool do_gemv = true) {
;     ...
;         if (r < I_SQ) { transpose_item(p.b_w_out, 2048, (bf16_t*)(ws + OFF_W_BOUT), 2048, r / 32, r % 32, scr, lane); continue; } r -= I_SQ;
.LBB0_48:
	s_andn2_b64 vcc, exec, s[0:1]
	s_cbranch_vccnz .LBB0_50
	s_lshl_b32 s0, s12, 1
	s_and_b32 s0, s0, 0x7fc0
	s_lshl_b32 s1, s12, 6
	s_addk_i32 s0, 0xb000
	s_and_b32 s10, s1, 0x7c0
	v_or_b32_e32 v2, s0, v88
	s_lshl_b32 s2, s10, 2
	v_lshl_add_u64 v[0:1], v[78:79], 0, s[2:3]
	v_lshlrev_b32_e32 v64, 11, v2
	v_lshl_add_u64 v[60:61], v[64:65], 2, v[0:1]
	v_add_co_u32_e32 v4, vcc, 0x8000, v60
	s_mov_b32 s1, s3
	s_nop 0
	v_addc_co_u32_e32 v5, vcc, 0, v61, vcc
	v_add_co_u32_e32 v8, vcc, 0x10000, v60
	global_load_dwordx4 v[0:3], v[60:61], off nt
	s_nop 0
	global_load_dwordx4 v[4:7], v[4:5], off nt
	v_addc_co_u32_e32 v9, vcc, 0, v61, vcc
	v_add_co_u32_e32 v12, vcc, 0x18000, v60
	s_nop 1
	v_addc_co_u32_e32 v13, vcc, 0, v61, vcc
	v_add_co_u32_e32 v16, vcc, 0x20000, v60
	global_load_dwordx4 v[8:11], v[8:9], off nt
	s_nop 0
	global_load_dwordx4 v[12:15], v[12:13], off nt
	v_addc_co_u32_e32 v17, vcc, 0, v61, vcc
	v_add_co_u32_e32 v20, vcc, 0x28000, v60
	s_nop 1
	v_addc_co_u32_e32 v21, vcc, 0, v61, vcc
	v_add_co_u32_e32 v24, vcc, 0x30000, v60
	global_load_dwordx4 v[16:19], v[16:17], off nt
	s_nop 0
	global_load_dwordx4 v[20:23], v[20:21], off nt
	v_addc_co_u32_e32 v25, vcc, 0, v61, vcc
	v_add_co_u32_e32 v28, vcc, 0x38000, v60
	s_nop 1
	v_addc_co_u32_e32 v29, vcc, 0, v61, vcc
	v_add_co_u32_e32 v32, vcc, 0x40000, v60
	global_load_dwordx4 v[24:27], v[24:25], off nt
	s_nop 0
	global_load_dwordx4 v[28:31], v[28:29], off nt
	v_addc_co_u32_e32 v33, vcc, 0, v61, vcc
	v_add_co_u32_e32 v36, vcc, 0x48000, v60
	s_nop 1
	v_addc_co_u32_e32 v37, vcc, 0, v61, vcc
	v_add_co_u32_e32 v40, vcc, 0x50000, v60
	global_load_dwordx4 v[32:35], v[32:33], off nt
	s_nop 0
	global_load_dwordx4 v[36:39], v[36:37], off nt
	v_addc_co_u32_e32 v41, vcc, 0, v61, vcc
	v_add_co_u32_e32 v44, vcc, 0x58000, v60
	s_nop 1
	v_addc_co_u32_e32 v45, vcc, 0, v61, vcc
	global_load_dwordx4 v[40:43], v[40:41], off nt
	s_nop 0
	global_load_dwordx4 v[44:47], v[44:45], off nt
	v_add_co_u32_e32 v48, vcc, 0x60000, v60
	s_nop 1
	v_addc_co_u32_e32 v49, vcc, 0, v61, vcc
	v_add_co_u32_e32 v52, vcc, 0x68000, v60
	s_nop 1
	v_addc_co_u32_e32 v53, vcc, 0, v61, vcc
	global_load_dwordx4 v[48:51], v[48:49], off nt
	s_nop 0
	global_load_dwordx4 v[52:55], v[52:53], off nt
	v_add_co_u32_e32 v56, vcc, 0x70000, v60
	s_nop 1
	v_addc_co_u32_e32 v57, vcc, 0, v61, vcc
	global_load_dwordx4 v[56:59], v[56:57], off nt
	v_add_co_u32_e32 v60, vcc, 0x78000, v60
	s_nop 1
	v_addc_co_u32_e32 v61, vcc, 0, v61, vcc
	global_load_dwordx4 v[60:63], v[60:61], off nt
	s_waitcnt vmcnt(15)
	ds_write2_b32 v89, v0, v1 offset1:1
	ds_write2_b32 v89, v2, v3 offset0:2 offset1:3
	s_waitcnt vmcnt(14)
	ds_write2_b32 v103, v4, v5 offset1:1
	ds_write2_b32 v104, v6, v7 offset1:1
	s_waitcnt vmcnt(13)
	ds_write2_b32 v105, v8, v9 offset1:1
	ds_write2_b32 v106, v10, v11 offset1:1
	s_waitcnt vmcnt(12)
	ds_write2_b32 v107, v12, v13 offset1:1
	ds_write2_b32 v108, v14, v15 offset1:1
	s_waitcnt vmcnt(11)
	ds_write2_b32 v109, v16, v17 offset1:1
	ds_write2_b32 v110, v18, v19 offset1:1
	s_waitcnt vmcnt(10)
	ds_write2_b32 v111, v20, v21 offset1:1
	ds_write2_b32 v112, v22, v23 offset1:1
	s_waitcnt vmcnt(9)
	ds_write2_b32 v113, v24, v25 offset1:1
	ds_write2_b32 v114, v26, v27 offset1:1
	s_waitcnt vmcnt(8)
	ds_write2_b32 v115, v28, v29 offset1:1
	ds_write2_b32 v116, v30, v31 offset1:1
	s_waitcnt vmcnt(7)
	ds_write2_b32 v117, v32, v33 offset1:1
	ds_write2_b32 v118, v34, v35 offset1:1
	v_add_u32_e32 v0, 0x2490, v89
	s_waitcnt vmcnt(6)
	ds_write2_b32 v0, v36, v37 offset1:1
	v_add_u32_e32 v0, 0x2498, v89
	ds_write2_b32 v0, v38, v39 offset1:1
	v_add_u32_e32 v0, 0x28a0, v89
	v_add_u32_e32 v24, 0x400, v91
	v_lshl_add_u64 v[20:21], s[0:1], 1, v[70:71]
	s_waitcnt vmcnt(5)
	ds_write2_b32 v0, v40, v41 offset1:1
	v_add_u32_e32 v0, 0x28a8, v89
	ds_write2_b32 v0, v42, v43 offset1:1
	v_add_u32_e32 v0, 0x2cb0, v89
	s_waitcnt vmcnt(4)
	ds_write2_b32 v0, v44, v45 offset1:1
	v_add_u32_e32 v0, 0x2cb8, v89
	ds_write2_b32 v0, v46, v47 offset1:1
	v_add_u32_e32 v0, 0x30c0, v89
	s_waitcnt vmcnt(3)
	ds_write2_b32 v0, v48, v49 offset1:1
	v_add_u32_e32 v0, 0x30c8, v89
	ds_write2_b32 v0, v50, v51 offset1:1
	v_add_u32_e32 v0, 0x34d0, v89
	s_waitcnt vmcnt(2)
	ds_write2_b32 v0, v52, v53 offset1:1
	v_add_u32_e32 v0, 0x34d8, v89
	ds_write2_b32 v0, v54, v55 offset1:1
	v_add_u32_e32 v0, 0x38e0, v89
	s_waitcnt vmcnt(1)
; #define LAS __attribute__((address_space(3)))
; __device__ __forceinline__ unsigned cvt_pk_bf16(float lo, float hi) { const bf16x2_t r = __builtin_convertvector((f32x2){lo, hi}, bf16x2_t); return __builtin_bit_cast(unsigned, r); }
; #define LDS_FENCE() asm volatile("s_waitcnt lgkmcnt(0)" ::: "memory")
; __device__ __forceinline__ void transpose_item(const float* src, int ldsrc, bf16_t* dst, int lddst, int kt, int ntile, LAS float* scr, int lane, const float* kscale = nullptr) {
;     ...
;     LDS_FENCE();
;     const int c = lane & 7;
; #pragma unroll
;     for (int j = 0; j < 8; ++j) { const int n = (lane >> 3) + 8 * j; const LAS float* s = scr + (8 * c) * 65 + n;
;         u32x4 o; o.x = cvt_pk_bf16(s[0], s[65]); o.y = cvt_pk_bf16(s[2 * 65], s[3 * 65]); o.z = cvt_pk_bf16(s[4 * 65], s[5 * 65]); o.w = cvt_pk_bf16(s[6 * 65], s[7 * 65]);
;         *(u32x4*)(dst + (size_t)(n0 + n) * lddst + k0 + 8 * c) = o; }
;     LDS_FENCE();
	ds_write2_b32 v0, v56, v57 offset1:1
	v_add_u32_e32 v0, 0x38e8, v89
	ds_write2_b32 v0, v58, v59 offset1:1
	v_add_u32_e32 v0, 0x3cf0, v89
	s_waitcnt vmcnt(0)
	ds_write2_b32 v0, v60, v61 offset1:1
	v_add_u32_e32 v0, 0x3cf8, v89
	ds_write2_b32 v0, v62, v63 offset1:1
	s_waitcnt lgkmcnt(0)
	ds_read2_b32 v[4:5], v91 offset0:65 offset1:73
	ds_read2_b32 v[6:7], v91 offset1:8
	ds_read2_b32 v[8:9], v91 offset0:130 offset1:138
	ds_read2_b32 v[10:11], v91 offset0:195 offset1:203
	ds_read2_b32 v[12:13], v24 offset0:4 offset1:12
	ds_read2_b32 v[14:15], v24 offset0:69 offset1:77
	ds_read2_b32 v[16:17], v24 offset0:134 offset1:142
	ds_read2_b32 v[18:19], v24 offset0:199 offset1:207
	s_waitcnt lgkmcnt(6)
	v_cvt_pk_bf16_f32 v0, v6, v4
	v_or_b32_e32 v4, s10, v90
	v_lshlrev_b32_e32 v64, 12, v4
	s_waitcnt lgkmcnt(4)
	v_cvt_pk_bf16_f32 v1, v8, v10
	s_waitcnt lgkmcnt(2)
	v_cvt_pk_bf16_f32 v2, v12, v14
	s_waitcnt lgkmcnt(0)
	v_cvt_pk_bf16_f32 v3, v16, v18
	v_lshl_add_u64 v[22:23], v[20:21], 0, v[64:65]
	global_store_dwordx4 v[22:23], v[0:3], off
	v_or_b32_e32 v4, s10, v92
	v_lshlrev_b32_e32 v64, 12, v4
	v_cvt_pk_bf16_f32 v0, v7, v5
	v_cvt_pk_bf16_f32 v1, v9, v11
	v_cvt_pk_bf16_f32 v2, v13, v15
	v_cvt_pk_bf16_f32 v3, v17, v19
	ds_read2_b32 v[6:7], v91 offset0:81 offset1:89
	ds_read2_b32 v[8:9], v91 offset0:16 offset1:24
	ds_read2_b32 v[10:11], v91 offset0:146 offset1:154
	ds_read2_b32 v[12:13], v91 offset0:211 offset1:219
	ds_read2_b32 v[14:15], v24 offset0:20 offset1:28
	ds_read2_b32 v[16:17], v24 offset0:85 offset1:93
	ds_read2_b32 v[18:19], v24 offset0:150 offset1:158
	ds_read2_b32 v[22:23], v24 offset0:215 offset1:223
	v_lshl_add_u64 v[4:5], v[20:21], 0, v[64:65]
	global_store_dwordx4 v[4:5], v[0:3], off
	v_or_b32_e32 v4, s10, v93
	v_lshlrev_b32_e32 v64, 12, v4
	s_waitcnt lgkmcnt(6)
	v_cvt_pk_bf16_f32 v0, v8, v6
	s_waitcnt lgkmcnt(4)
	v_cvt_pk_bf16_f32 v1, v10, v12
	s_waitcnt lgkmcnt(2)
	v_cvt_pk_bf16_f32 v2, v14, v16
	s_waitcnt lgkmcnt(0)
	v_cvt_pk_bf16_f32 v3, v18, v22
	v_lshl_add_u64 v[4:5], v[20:21], 0, v[64:65]
	global_store_dwordx4 v[4:5], v[0:3], off
	v_or_b32_e32 v4, s10, v94
	v_lshlrev_b32_e32 v64, 12, v4
	v_cvt_pk_bf16_f32 v0, v9, v7
	v_cvt_pk_bf16_f32 v1, v11, v13
	v_cvt_pk_bf16_f32 v2, v15, v17
	v_cvt_pk_bf16_f32 v3, v19, v23
	ds_read2_b32 v[6:7], v91 offset0:32 offset1:40
	ds_read2_b32 v[8:9], v91 offset0:97 offset1:105
	ds_read2_b32 v[10:11], v91 offset0:162 offset1:170
	ds_read2_b32 v[12:13], v91 offset0:227 offset1:235
	ds_read2_b32 v[14:15], v24 offset0:36 offset1:44
	ds_read2_b32 v[16:17], v24 offset0:101 offset1:109
	ds_read2_b32 v[18:19], v24 offset0:166 offset1:174
	ds_read2_b32 v[22:23], v24 offset0:231 offset1:239
	v_lshl_add_u64 v[4:5], v[20:21], 0, v[64:65]
	global_store_dwordx4 v[4:5], v[0:3], off
	v_or_b32_e32 v4, s10, v95
	v_lshlrev_b32_e32 v64, 12, v4
	s_waitcnt lgkmcnt(6)
	v_cvt_pk_bf16_f32 v0, v6, v8
	s_waitcnt lgkmcnt(4)
	v_cvt_pk_bf16_f32 v1, v10, v12
	s_waitcnt lgkmcnt(2)
	v_cvt_pk_bf16_f32 v2, v14, v16
	s_waitcnt lgkmcnt(0)
	v_cvt_pk_bf16_f32 v3, v18, v22
	v_lshl_add_u64 v[4:5], v[20:21], 0, v[64:65]
	global_store_dwordx4 v[4:5], v[0:3], off
	v_or_b32_e32 v4, s10, v96
	v_lshlrev_b32_e32 v64, 12, v4
	v_cvt_pk_bf16_f32 v0, v7, v9
	v_cvt_pk_bf16_f32 v1, v11, v13
	v_cvt_pk_bf16_f32 v2, v15, v17
	v_cvt_pk_bf16_f32 v3, v19, v23
	ds_read2_b32 v[6:7], v91 offset0:48 offset1:56
	ds_read2_b32 v[8:9], v91 offset0:113 offset1:121
	ds_read2_b32 v[10:11], v91 offset0:178 offset1:186
	ds_read2_b32 v[12:13], v91 offset0:243 offset1:251
	ds_read2_b32 v[14:15], v24 offset0:52 offset1:60
	ds_read2_b32 v[16:17], v24 offset0:117 offset1:125
	ds_read2_b32 v[18:19], v24 offset0:182 offset1:190
	ds_read2_b32 v[22:23], v24 offset0:247 offset1:255
	v_lshl_add_u64 v[4:5], v[20:21], 0, v[64:65]
	global_store_dwordx4 v[4:5], v[0:3], off
	v_or_b32_e32 v4, s10, v97
	v_lshlrev_b32_e32 v64, 12, v4
	s_waitcnt lgkmcnt(6)
	v_cvt_pk_bf16_f32 v0, v6, v8
	s_waitcnt lgkmcnt(4)
	v_cvt_pk_bf16_f32 v1, v10, v12
	s_waitcnt lgkmcnt(2)
	v_cvt_pk_bf16_f32 v2, v14, v16
	s_waitcnt lgkmcnt(0)
	v_cvt_pk_bf16_f32 v3, v18, v22
	v_lshl_add_u64 v[4:5], v[20:21], 0, v[64:65]
	global_store_dwordx4 v[4:5], v[0:3], off
	v_or_b32_e32 v4, s10, v98
	v_lshlrev_b32_e32 v64, 12, v4
	v_cvt_pk_bf16_f32 v0, v7, v9
	v_cvt_pk_bf16_f32 v1, v11, v13
	v_cvt_pk_bf16_f32 v2, v15, v17
	v_cvt_pk_bf16_f32 v3, v19, v23
	v_lshl_add_u64 v[4:5], v[20:21], 0, v[64:65]
	global_store_dwordx4 v[4:5], v[0:3], off
	s_waitcnt lgkmcnt(0)

; #define LAS __attribute__((address_space(3)))
; __device__ __forceinline__ void transpose_item(const float* src, int ldsrc, bf16_t* dst, int lddst, int kt, int ntile, LAS float* scr, int lane, const float* kscale = nullptr) {
;     const int k0 = kt * 64, n0 = ntile * 64, l16 = lane & 15, l4 = lane >> 4;
;     f32x4 tv[16];
; #pragma unroll
;     for (int i = 0; i < 16; ++i) tv[i] = *(const f32x4*)(src + (size_t)(k0 + l4 + 4 * i) * ldsrc + n0 + 4 * l16);
;     if (kscale) {
; #pragma unroll
;         for (int i = 0; i < 16; ++i) tv[i] *= kscale[k0 + l4 + 4 * i];
;     }
; __device__ __forceinline__ void phase0(const Params& p, LAS unsigned char* lds, const bool do_gemv = true) {
;     ...
;         if (r < I_SQ) { transpose_item(p.a_w_out, 2048, (bf16_t*)(ws + OFF_W_AOUT), 2048, r / 32, r % 32, scr, lane, p.a_norm_g); continue; } r -= I_SQ;
.LBB0_51:
	s_andn2_b64 vcc, exec, s[0:1]
	s_cbranch_vccnz .LBB0_55
	s_lshl_b32 s0, s12, 1
	s_and_b32 s0, s0, 0x7fc0
	s_lshl_b32 s1, s12, 6
	s_addk_i32 s0, 0xb800
	s_and_b32 s10, s1, 0x7c0
	v_or_b32_e32 v86, s0, v88
	s_lshl_b32 s2, s10, 2
	v_lshl_add_u64 v[52:53], v[80:81], 0, s[2:3]
	v_lshlrev_b32_e32 v64, 11, v86
	v_lshl_add_u64 v[0:1], v[64:65], 2, v[52:53]
	v_or_b32_e32 v2, 0x2000, v64
	v_mov_b32_e32 v3, v65
	v_or_b32_e32 v8, 0x4000, v64
	v_mov_b32_e32 v9, v65
	v_or_b32_e32 v10, 0x6000, v64
	v_mov_b32_e32 v11, v65
	v_or_b32_e32 v16, 0x8000, v64
	v_mov_b32_e32 v17, v65
	v_or_b32_e32 v18, 0xa000, v64
	v_mov_b32_e32 v19, v65
	v_or_b32_e32 v24, 0xc000, v64
	v_mov_b32_e32 v25, v65
	v_or_b32_e32 v26, 0xe000, v64
	v_mov_b32_e32 v27, v65
	v_or_b32_e32 v32, 0x10000, v64
	v_mov_b32_e32 v33, v65
	v_or_b32_e32 v34, 0x12000, v64
	v_mov_b32_e32 v35, v65
	v_or_b32_e32 v36, 0x14000, v64
	v_mov_b32_e32 v37, v65
	v_or_b32_e32 v38, 0x16000, v64
	v_mov_b32_e32 v39, v65
	v_or_b32_e32 v44, 0x18000, v64
	v_mov_b32_e32 v45, v65
	v_or_b32_e32 v46, 0x1a000, v64
	v_mov_b32_e32 v47, v65
	v_or_b32_e32 v54, 0x1c000, v64
	v_mov_b32_e32 v55, v65
	v_or_b32_e32 v64, 0x1e000, v64
	v_lshl_add_u64 v[2:3], v[2:3], 2, v[52:53]
	v_lshl_add_u64 v[8:9], v[8:9], 2, v[52:53]
	v_lshl_add_u64 v[10:11], v[10:11], 2, v[52:53]
	v_lshl_add_u64 v[16:17], v[16:17], 2, v[52:53]
	v_lshl_add_u64 v[18:19], v[18:19], 2, v[52:53]
	v_lshl_add_u64 v[24:25], v[24:25], 2, v[52:53]
	v_lshl_add_u64 v[26:27], v[26:27], 2, v[52:53]
	v_lshl_add_u64 v[32:33], v[32:33], 2, v[52:53]
	v_lshl_add_u64 v[34:35], v[34:35], 2, v[52:53]
	v_lshl_add_u64 v[36:37], v[36:37], 2, v[52:53]
	v_lshl_add_u64 v[38:39], v[38:39], 2, v[52:53]
	v_lshl_add_u64 v[44:45], v[44:45], 2, v[52:53]
	v_lshl_add_u64 v[46:47], v[46:47], 2, v[52:53]
	v_lshl_add_u64 v[54:55], v[54:55], 2, v[52:53]
	v_lshl_add_u64 v[52:53], v[64:65], 2, v[52:53]
	global_load_dwordx4 v[4:7], v[0:1], off nt
	s_nop 0
	global_load_dwordx4 v[0:3], v[2:3], off nt
	s_nop 0
	global_load_dwordx4 v[12:15], v[8:9], off nt
	s_nop 0
	global_load_dwordx4 v[8:11], v[10:11], off nt
	s_nop 0
	global_load_dwordx4 v[20:23], v[16:17], off nt
	s_nop 0
	global_load_dwordx4 v[16:19], v[18:19], off nt
	s_nop 0
	global_load_dwordx4 v[28:31], v[24:25], off nt
	s_nop 0
	global_load_dwordx4 v[24:27], v[26:27], off nt
	s_nop 0
	global_load_dwordx4 v[40:43], v[32:33], off nt
	s_nop 0
	global_load_dwordx4 v[32:35], v[34:35], off nt
	s_nop 0
	global_load_dwordx4 v[48:51], v[36:37], off nt
	s_nop 0
	global_load_dwordx4 v[36:39], v[38:39], off nt
	s_nop 0
	global_load_dwordx4 v[56:59], v[44:45], off nt
	s_nop 0
	global_load_dwordx4 v[44:47], v[46:47], off nt
	s_nop 0
	global_load_dwordx4 v[60:63], v[54:55], off nt
	s_nop 0
	global_load_dwordx4 v[52:55], v[52:53], off nt
	s_andn2_b64 vcc, exec, s[8:9]
	s_cbranch_vccnz .LBB0_54
	v_mov_b32_e32 v87, v65
	v_lshl_add_u64 v[86:87], v[86:87], 2, s[92:93]
	global_load_dword v64, v[86:87], off
	global_load_dword v120, v[86:87], off offset:16
	global_load_dword v122, v[86:87], off offset:32
	global_load_dword v124, v[86:87], off offset:48
	global_load_dword v126, v[86:87], off offset:64
	global_load_dword v128, v[86:87], off offset:80
	global_load_dword v130, v[86:87], off offset:96
	global_load_dword v132, v[86:87], off offset:112
	global_load_dword v134, v[86:87], off offset:128
	global_load_dword v136, v[86:87], off offset:144
	global_load_dword v138, v[86:87], off offset:160
	global_load_dword v140, v[86:87], off offset:176
	global_load_dword v142, v[86:87], off offset:192
	global_load_dword v144, v[86:87], off offset:208
	global_load_dword v146, v[86:87], off offset:224
	s_nop 0
	global_load_dword v86, v[86:87], off offset:240
	s_waitcnt vmcnt(15)
	v_pk_mul_f32 v[6:7], v[6:7], v[64:65] op_sel_hi:[1,0]
	v_pk_mul_f32 v[4:5], v[4:5], v[64:65] op_sel_hi:[1,0]
	s_waitcnt vmcnt(14)
	v_pk_mul_f32 v[2:3], v[2:3], v[120:121] op_sel_hi:[1,0]
	v_pk_mul_f32 v[0:1], v[0:1], v[120:121] op_sel_hi:[1,0]
	s_waitcnt vmcnt(13)
	v_pk_mul_f32 v[14:15], v[14:15], v[122:123] op_sel_hi:[1,0]
	v_pk_mul_f32 v[12:13], v[12:13], v[122:123] op_sel_hi:[1,0]
	s_waitcnt vmcnt(12)
	v_pk_mul_f32 v[10:11], v[10:11], v[124:125] op_sel_hi:[1,0]
	v_pk_mul_f32 v[8:9], v[8:9], v[124:125] op_sel_hi:[1,0]
	s_waitcnt vmcnt(11)
	v_pk_mul_f32 v[22:23], v[22:23], v[126:127] op_sel_hi:[1,0]
	v_pk_mul_f32 v[20:21], v[20:21], v[126:127] op_sel_hi:[1,0]
	s_waitcnt vmcnt(10)
	v_pk_mul_f32 v[18:19], v[18:19], v[128:129] op_sel_hi:[1,0]
	v_pk_mul_f32 v[16:17], v[16:17], v[128:129] op_sel_hi:[1,0]
	s_waitcnt vmcnt(9)
	v_pk_mul_f32 v[30:31], v[30:31], v[130:131] op_sel_hi:[1,0]
	v_pk_mul_f32 v[28:29], v[28:29], v[130:131] op_sel_hi:[1,0]
	s_waitcnt vmcnt(8)
	v_pk_mul_f32 v[26:27], v[26:27], v[132:133] op_sel_hi:[1,0]
	v_pk_mul_f32 v[24:25], v[24:25], v[132:133] op_sel_hi:[1,0]
	s_waitcnt vmcnt(7)
	v_pk_mul_f32 v[42:43], v[42:43], v[134:135] op_sel_hi:[1,0]
	v_pk_mul_f32 v[40:41], v[40:41], v[134:135] op_sel_hi:[1,0]
	s_waitcnt vmcnt(6)
	v_pk_mul_f32 v[34:35], v[34:35], v[136:137] op_sel_hi:[1,0]
	v_pk_mul_f32 v[32:33], v[32:33], v[136:137] op_sel_hi:[1,0]
	s_waitcnt vmcnt(5)
	v_pk_mul_f32 v[50:51], v[50:51], v[138:139] op_sel_hi:[1,0]
	v_pk_mul_f32 v[48:49], v[48:49], v[138:139] op_sel_hi:[1,0]
	s_waitcnt vmcnt(4)
	v_pk_mul_f32 v[38:39], v[38:39], v[140:141] op_sel_hi:[1,0]
	v_pk_mul_f32 v[36:37], v[36:37], v[140:141] op_sel_hi:[1,0]
	s_waitcnt vmcnt(3)
	v_pk_mul_f32 v[58:59], v[58:59], v[142:143] op_sel_hi:[1,0]
	v_pk_mul_f32 v[56:57], v[56:57], v[142:143] op_sel_hi:[1,0]
	s_waitcnt vmcnt(2)
	v_pk_mul_f32 v[46:47], v[46:47], v[144:145] op_sel_hi:[1,0]
	v_pk_mul_f32 v[44:45], v[44:45], v[144:145] op_sel_hi:[1,0]
	s_waitcnt vmcnt(1)
	v_pk_mul_f32 v[62:63], v[62:63], v[146:147] op_sel_hi:[1,0]
	v_pk_mul_f32 v[60:61], v[60:61], v[146:147] op_sel_hi:[1,0]
	s_waitcnt vmcnt(0)
	v_pk_mul_f32 v[54:55], v[54:55], v[86:87] op_sel_hi:[1,0]
	v_pk_mul_f32 v[52:53], v[52:53], v[86:87] op_sel_hi:[1,0]

; #define LAS __attribute__((address_space(3)))
; __device__ __forceinline__ void transpose_item(const float* src, int ldsrc, bf16_t* dst, int lddst, int kt, int ntile, LAS float* scr, int lane, const float* kscale = nullptr) {
;     const int k0 = kt * 64, n0 = ntile * 64, l16 = lane & 15, l4 = lane >> 4;
;     f32x4 tv[16];
; #pragma unroll
;     for (int i = 0; i < 16; ++i) tv[i] = *(const f32x4*)(src + (size_t)(k0 + l4 + 4 * i) * ldsrc + n0 + 4 * l16);
;     if (kscale) {
; #pragma unroll
;         for (int i = 0; i < 16; ++i) tv[i] *= kscale[k0 + l4 + 4 * i];
;     }
; #pragma unroll
;     for (int i = 0; i < 16; ++i) { const int kk = l4 + 4 * i; const f32x4 v = tv[i];
;         LAS float* d = scr + kk * 65 + 4 * l16; d[0] = v[0]; d[1] = v[1]; d[2] = v[2]; d[3] = v[3]; }
; __device__ __forceinline__ void phase0(const Params& p, LAS unsigned char* lds, const bool do_gemv = true) {
;     ...
;         if (r < I_AIN) { transpose_item(p.a_w_in, INA, (bf16_t*)(ws + OFF_W_AIN), 2048, r / 96, r % 96, scr, lane); continue; } r -= I_AIN;
.LBB0_56:
	s_andn2_b64 vcc, exec, s[0:1]
	s_cbranch_vccnz .LBB0_58
	s_add_i32 s0, s12, 0xe800
	s_and_b32 s1, s0, 0xffff
	s_mul_i32 s1, s1, 0xaaab
	s_lshr_b32 s2, s1, 16
	s_lshr_b32 s1, s1, 22
	s_mulk_i32 s1, 0x60
	s_sub_i32 s0, s0, s1
	s_and_b32 s1, s2, 0xffc0
	s_lshl_b32 s0, s0, 6
	s_and_b32 s0, s0, 0xffc0
	v_or_b32_e32 v2, s1, v88
	s_lshl_b32 s2, s0, 2
	v_mul_u32_u24_e32 v2, 0x1810, v2
	v_lshl_add_u64 v[0:1], v[82:83], 0, s[2:3]
	v_lshlrev_b32_e32 v64, 2, v2
	v_lshl_add_u64 v[60:61], v[0:1], 0, v[64:65]
	v_add_co_u32_e32 v4, vcc, s23, v60
	s_lshl_b32 s2, s1, 1
	s_nop 0
	v_addc_co_u32_e32 v5, vcc, 0, v61, vcc
	v_add_co_u32_e32 v8, vcc, s25, v60
	global_load_dwordx4 v[0:3], v[60:61], off nt
	s_nop 0
	global_load_dwordx4 v[4:7], v[4:5], off offset:256 nt
	v_addc_co_u32_e32 v9, vcc, 0, v61, vcc
	v_add_co_u32_e32 v12, vcc, s27, v60
	s_nop 1
	v_addc_co_u32_e32 v13, vcc, 0, v61, vcc
	v_add_co_u32_e32 v16, vcc, s28, v60
	global_load_dwordx4 v[8:11], v[8:9], off offset:512 nt
	s_nop 0
	global_load_dwordx4 v[12:15], v[12:13], off offset:768 nt
	v_addc_co_u32_e32 v17, vcc, 0, v61, vcc
	v_add_co_u32_e32 v20, vcc, s29, v60
	s_nop 1
	v_addc_co_u32_e32 v21, vcc, 0, v61, vcc
	v_add_co_u32_e32 v24, vcc, s33, v60
	global_load_dwordx4 v[16:19], v[16:17], off offset:1024 nt
	s_nop 0
	global_load_dwordx4 v[20:23], v[20:21], off offset:1280 nt
	v_addc_co_u32_e32 v25, vcc, 0, v61, vcc
	v_add_co_u32_e32 v28, vcc, s37, v60
	s_nop 1
	v_addc_co_u32_e32 v29, vcc, 0, v61, vcc
	v_add_co_u32_e32 v32, vcc, s30, v60
	global_load_dwordx4 v[24:27], v[24:25], off offset:1536 nt
	s_nop 0
	global_load_dwordx4 v[28:31], v[28:29], off offset:1792 nt
	v_addc_co_u32_e32 v33, vcc, 0, v61, vcc
	v_add_co_u32_e32 v36, vcc, s38, v60
	s_nop 1
	v_addc_co_u32_e32 v37, vcc, 0, v61, vcc
	v_add_co_u32_e32 v40, vcc, s34, v60
	global_load_dwordx4 v[32:35], v[32:33], off offset:2048 nt
	s_nop 0
	global_load_dwordx4 v[36:39], v[36:37], off offset:2304 nt
	v_addc_co_u32_e32 v41, vcc, 0, v61, vcc
	v_add_co_u32_e32 v44, vcc, s39, v60
	s_nop 1
	v_addc_co_u32_e32 v45, vcc, 0, v61, vcc
	global_load_dwordx4 v[40:43], v[40:41], off offset:2560 nt
	s_nop 0
	global_load_dwordx4 v[44:47], v[44:45], off offset:2816 nt
	v_add_co_u32_e32 v48, vcc, s31, v60
	s_nop 1
	v_addc_co_u32_e32 v49, vcc, 0, v61, vcc
	global_load_dwordx4 v[48:51], v[48:49], off offset:3072 nt
	v_add_co_u32_e32 v52, vcc, s40, v60
	s_nop 1
	v_addc_co_u32_e32 v53, vcc, 0, v61, vcc
	global_load_dwordx4 v[52:55], v[52:53], off offset:3328 nt
	v_add_co_u32_e32 v56, vcc, s41, v60
	s_nop 1
	v_addc_co_u32_e32 v57, vcc, 0, v61, vcc
	global_load_dwordx4 v[56:59], v[56:57], off offset:3584 nt
	v_add_co_u32_e32 v60, vcc, s42, v60
	s_nop 1
	v_addc_co_u32_e32 v61, vcc, 0, v61, vcc
	global_load_dwordx4 v[60:63], v[60:61], off offset:3840 nt
	s_waitcnt vmcnt(15)
	ds_write2_b32 v89, v0, v1 offset1:1
	ds_write2_b32 v89, v2, v3 offset0:2 offset1:3
	s_waitcnt vmcnt(14)
	ds_write2_b32 v103, v4, v5 offset1:1
	ds_write2_b32 v104, v6, v7 offset1:1
	s_waitcnt vmcnt(13)
	ds_write2_b32 v105, v8, v9 offset1:1
	ds_write2_b32 v106, v10, v11 offset1:1
	s_waitcnt vmcnt(12)
	ds_write2_b32 v107, v12, v13 offset1:1
	ds_write2_b32 v108, v14, v15 offset1:1
	s_waitcnt vmcnt(11)
	ds_write2_b32 v109, v16, v17 offset1:1
	ds_write2_b32 v110, v18, v19 offset1:1
	s_waitcnt vmcnt(10)
	ds_write2_b32 v111, v20, v21 offset1:1
	ds_write2_b32 v112, v22, v23 offset1:1
	s_waitcnt vmcnt(9)
	ds_write2_b32 v113, v24, v25 offset1:1
	ds_write2_b32 v114, v26, v27 offset1:1
	s_waitcnt vmcnt(8)
	ds_write2_b32 v115, v28, v29 offset1:1
	ds_write2_b32 v116, v30, v31 offset1:1
	s_waitcnt vmcnt(7)
	ds_write2_b32 v117, v32, v33 offset1:1
	ds_write2_b32 v118, v34, v35 offset1:1
	v_add_u32_e32 v0, 0x2490, v89
	s_waitcnt vmcnt(6)
	ds_write2_b32 v0, v36, v37 offset1:1
	v_add_u32_e32 v0, 0x2498, v89
	ds_write2_b32 v0, v38, v39 offset1:1
	v_add_u32_e32 v0, 0x28a0, v89
	v_add_u32_e32 v24, 0x400, v91
	v_lshl_add_u64 v[20:21], v[74:75], 0, s[2:3]
	s_waitcnt vmcnt(5)
	ds_write2_b32 v0, v40, v41 offset1:1
	v_add_u32_e32 v0, 0x28a8, v89
	ds_write2_b32 v0, v42, v43 offset1:1
	v_add_u32_e32 v0, 0x2cb0, v89
	s_waitcnt vmcnt(4)
	ds_write2_b32 v0, v44, v45 offset1:1
	v_add_u32_e32 v0, 0x2cb8, v89
	ds_write2_b32 v0, v46, v47 offset1:1
	v_add_u32_e32 v0, 0x30c0, v89
	s_waitcnt vmcnt(3)
	ds_write2_b32 v0, v48, v49 offset1:1
	v_add_u32_e32 v0, 0x30c8, v89
	ds_write2_b32 v0, v50, v51 offset1:1
	v_add_u32_e32 v0, 0x34d0, v89
	s_waitcnt vmcnt(2)
; #define LAS __attribute__((address_space(3)))
; __device__ __forceinline__ unsigned cvt_pk_bf16(float lo, float hi) { const bf16x2_t r = __builtin_convertvector((f32x2){lo, hi}, bf16x2_t); return __builtin_bit_cast(unsigned, r); }
; #define LDS_FENCE() asm volatile("s_waitcnt lgkmcnt(0)" ::: "memory")
; __device__ __forceinline__ void transpose_item(const float* src, int ldsrc, bf16_t* dst, int lddst, int kt, int ntile, LAS float* scr, int lane, const float* kscale = nullptr) {
;     ...
;     for (int i = 0; i < 16; ++i) { const int kk = l4 + 4 * i; const f32x4 v = tv[i];
;         LAS float* d = scr + kk * 65 + 4 * l16; d[0] = v[0]; d[1] = v[1]; d[2] = v[2]; d[3] = v[3]; }
;     LDS_FENCE();
;     const int c = lane & 7;
; #pragma unroll
;     for (int j = 0; j < 8; ++j) { const int n = (lane >> 3) + 8 * j; const LAS float* s = scr + (8 * c) * 65 + n;
;         u32x4 o; o.x = cvt_pk_bf16(s[0], s[65]); o.y = cvt_pk_bf16(s[2 * 65], s[3 * 65]); o.z = cvt_pk_bf16(s[4 * 65], s[5 * 65]); o.w = cvt_pk_bf16(s[6 * 65], s[7 * 65]);
;         *(u32x4*)(dst + (size_t)(n0 + n) * lddst + k0 + 8 * c) = o; }
;     LDS_FENCE();
	ds_write2_b32 v0, v52, v53 offset1:1
	v_add_u32_e32 v0, 0x34d8, v89
	ds_write2_b32 v0, v54, v55 offset1:1
	v_add_u32_e32 v0, 0x38e0, v89
	s_waitcnt vmcnt(1)
	ds_write2_b32 v0, v56, v57 offset1:1
	v_add_u32_e32 v0, 0x38e8, v89
	ds_write2_b32 v0, v58, v59 offset1:1
	v_add_u32_e32 v0, 0x3cf0, v89
	s_waitcnt vmcnt(0)
	ds_write2_b32 v0, v60, v61 offset1:1
	v_add_u32_e32 v0, 0x3cf8, v89
	ds_write2_b32 v0, v62, v63 offset1:1
	s_waitcnt lgkmcnt(0)
	ds_read2_b32 v[4:5], v91 offset0:65 offset1:73
	ds_read2_b32 v[6:7], v91 offset1:8
	ds_read2_b32 v[8:9], v91 offset0:130 offset1:138
	ds_read2_b32 v[10:11], v91 offset0:195 offset1:203
	ds_read2_b32 v[12:13], v24 offset0:4 offset1:12
	ds_read2_b32 v[14:15], v24 offset0:69 offset1:77
	ds_read2_b32 v[16:17], v24 offset0:134 offset1:142
	ds_read2_b32 v[18:19], v24 offset0:199 offset1:207
	s_waitcnt lgkmcnt(6)
	v_cvt_pk_bf16_f32 v0, v6, v4
	v_or_b32_e32 v4, s0, v90
	v_lshlrev_b32_e32 v64, 12, v4
	s_waitcnt lgkmcnt(4)
	v_cvt_pk_bf16_f32 v1, v8, v10
	s_waitcnt lgkmcnt(2)
	v_cvt_pk_bf16_f32 v2, v12, v14
	s_waitcnt lgkmcnt(0)
	v_cvt_pk_bf16_f32 v3, v16, v18
	v_lshl_add_u64 v[22:23], v[20:21], 0, v[64:65]
	global_store_dwordx4 v[22:23], v[0:3], off
	v_or_b32_e32 v4, s0, v92
	v_lshlrev_b32_e32 v64, 12, v4
	v_cvt_pk_bf16_f32 v0, v7, v5
	v_cvt_pk_bf16_f32 v1, v9, v11
	v_cvt_pk_bf16_f32 v2, v13, v15
	v_cvt_pk_bf16_f32 v3, v17, v19
	ds_read2_b32 v[6:7], v91 offset0:81 offset1:89
	ds_read2_b32 v[8:9], v91 offset0:16 offset1:24
	ds_read2_b32 v[10:11], v91 offset0:146 offset1:154
	ds_read2_b32 v[12:13], v91 offset0:211 offset1:219
	ds_read2_b32 v[14:15], v24 offset0:20 offset1:28
	ds_read2_b32 v[16:17], v24 offset0:85 offset1:93
	ds_read2_b32 v[18:19], v24 offset0:150 offset1:158
	ds_read2_b32 v[22:23], v24 offset0:215 offset1:223
	v_lshl_add_u64 v[4:5], v[20:21], 0, v[64:65]
	global_store_dwordx4 v[4:5], v[0:3], off
	v_or_b32_e32 v4, s0, v93
	v_lshlrev_b32_e32 v64, 12, v4
	s_waitcnt lgkmcnt(6)
	v_cvt_pk_bf16_f32 v0, v8, v6
	s_waitcnt lgkmcnt(4)
	v_cvt_pk_bf16_f32 v1, v10, v12
	s_waitcnt lgkmcnt(2)
	v_cvt_pk_bf16_f32 v2, v14, v16
	s_waitcnt lgkmcnt(0)
	v_cvt_pk_bf16_f32 v3, v18, v22
	v_lshl_add_u64 v[4:5], v[20:21], 0, v[64:65]
	global_store_dwordx4 v[4:5], v[0:3], off
	v_or_b32_e32 v4, s0, v94
	v_lshlrev_b32_e32 v64, 12, v4
	v_cvt_pk_bf16_f32 v0, v9, v7
	v_cvt_pk_bf16_f32 v1, v11, v13
	v_cvt_pk_bf16_f32 v2, v15, v17
	v_cvt_pk_bf16_f32 v3, v19, v23
	ds_read2_b32 v[6:7], v91 offset0:32 offset1:40
	ds_read2_b32 v[8:9], v91 offset0:97 offset1:105
	ds_read2_b32 v[10:11], v91 offset0:162 offset1:170
	ds_read2_b32 v[12:13], v91 offset0:227 offset1:235
	ds_read2_b32 v[14:15], v24 offset0:36 offset1:44
	ds_read2_b32 v[16:17], v24 offset0:101 offset1:109
	ds_read2_b32 v[18:19], v24 offset0:166 offset1:174
	ds_read2_b32 v[22:23], v24 offset0:231 offset1:239
	v_lshl_add_u64 v[4:5], v[20:21], 0, v[64:65]
	global_store_dwordx4 v[4:5], v[0:3], off
	v_or_b32_e32 v4, s0, v95
	v_lshlrev_b32_e32 v64, 12, v4
	s_waitcnt lgkmcnt(6)
	v_cvt_pk_bf16_f32 v0, v6, v8
	s_waitcnt lgkmcnt(4)
	v_cvt_pk_bf16_f32 v1, v10, v12
	s_waitcnt lgkmcnt(2)
	v_cvt_pk_bf16_f32 v2, v14, v16
	s_waitcnt lgkmcnt(0)
	v_cvt_pk_bf16_f32 v3, v18, v22
	v_lshl_add_u64 v[4:5], v[20:21], 0, v[64:65]
	global_store_dwordx4 v[4:5], v[0:3], off
	v_or_b32_e32 v4, s0, v96
	v_lshlrev_b32_e32 v64, 12, v4
	v_cvt_pk_bf16_f32 v0, v7, v9
	v_cvt_pk_bf16_f32 v1, v11, v13
	v_cvt_pk_bf16_f32 v2, v15, v17
	v_cvt_pk_bf16_f32 v3, v19, v23
	ds_read2_b32 v[6:7], v91 offset0:48 offset1:56
	ds_read2_b32 v[8:9], v91 offset0:113 offset1:121
	ds_read2_b32 v[10:11], v91 offset0:178 offset1:186
	ds_read2_b32 v[12:13], v91 offset0:243 offset1:251
	ds_read2_b32 v[14:15], v24 offset0:52 offset1:60
	ds_read2_b32 v[16:17], v24 offset0:117 offset1:125
	ds_read2_b32 v[18:19], v24 offset0:182 offset1:190
	ds_read2_b32 v[22:23], v24 offset0:247 offset1:255
	v_lshl_add_u64 v[4:5], v[20:21], 0, v[64:65]
	global_store_dwordx4 v[4:5], v[0:3], off
	v_or_b32_e32 v4, s0, v97
	v_lshlrev_b32_e32 v64, 12, v4
	s_waitcnt lgkmcnt(6)
	v_cvt_pk_bf16_f32 v0, v6, v8
	s_waitcnt lgkmcnt(4)
	v_cvt_pk_bf16_f32 v1, v10, v12
	s_waitcnt lgkmcnt(2)
	v_cvt_pk_bf16_f32 v2, v14, v16
	s_waitcnt lgkmcnt(0)
	v_cvt_pk_bf16_f32 v3, v18, v22
	v_lshl_add_u64 v[4:5], v[20:21], 0, v[64:65]
	global_store_dwordx4 v[4:5], v[0:3], off
	v_or_b32_e32 v4, s0, v98
	v_lshlrev_b32_e32 v64, 12, v4
	v_cvt_pk_bf16_f32 v0, v7, v9
	v_cvt_pk_bf16_f32 v1, v11, v13
	v_cvt_pk_bf16_f32 v2, v15, v17
	v_cvt_pk_bf16_f32 v3, v19, v23
	v_lshl_add_u64 v[4:5], v[20:21], 0, v[64:65]
	global_store_dwordx4 v[4:5], v[0:3], off
	s_waitcnt lgkmcnt(0)

; __device__ __forceinline__ void gemv_item(const Params& p, unsigned long long* MOD, int it, LAS float* scr, int lane) {
;     ...
;     const float* W = p.ada_w + (size_t)mat * DM * 6144 + (size_t)k0 * 6144 + n0;
;     f32x4 a0 = {0, 0, 0, 0}, a1 = a0, a2 = a0, a3 = a0;
; #pragma unroll 16
;     for (int kk = 0; kk < 32; ++kk) { const f32x4 w = *(const f32x4*)(W + (size_t)kk * 6144);
;         a0 += w * scr[kk]; a1 += w * scr[32 + kk]; a2 += w * scr[64 + kk]; a3 += w * scr[96 + kk]; }
.LBB0_61:
	v_lshl_add_u64 v[44:45], v[18:19], 0, s[10:11]
	global_load_dwordx4 v[148:151], v[44:45], off nt
	v_add_co_u32_e32 v218, vcc, s20, v44
	s_nop 1
	v_addc_co_u32_e32 v219, vcc, 0, v45, vcc
	global_load_dwordx4 v[152:155], v[218:219], off nt
	v_add_co_u32_e32 v218, vcc, s22, v44
	s_nop 1
	v_addc_co_u32_e32 v219, vcc, 0, v45, vcc
	global_load_dwordx4 v[156:159], v[218:219], off nt
	v_add_co_u32_e32 v218, vcc, s35, v44
	s_nop 1
	v_addc_co_u32_e32 v219, vcc, 0, v45, vcc
	global_load_dwordx4 v[160:163], v[218:219], off nt
	v_add_co_u32_e32 v218, vcc, s23, v44
	s_nop 1
	v_addc_co_u32_e32 v219, vcc, 0, v45, vcc
	global_load_dwordx4 v[164:167], v[218:219], off nt
	v_add_co_u32_e32 v218, vcc, s36, v44
	s_nop 1
	v_addc_co_u32_e32 v219, vcc, 0, v45, vcc
	global_load_dwordx4 v[168:171], v[218:219], off nt
	v_add_co_u32_e32 v218, vcc, s43, v44
	s_nop 1
	v_addc_co_u32_e32 v219, vcc, 0, v45, vcc
	global_load_dwordx4 v[172:175], v[218:219], off nt
	v_add_co_u32_e32 v218, vcc, s44, v44
	s_nop 1
	v_addc_co_u32_e32 v219, vcc, 0, v45, vcc
	global_load_dwordx4 v[176:179], v[218:219], off nt
	v_add_co_u32_e32 v218, vcc, s25, v44
	s_nop 1
	v_addc_co_u32_e32 v219, vcc, 0, v45, vcc
	global_load_dwordx4 v[180:183], v[218:219], off nt
	v_add_co_u32_e32 v218, vcc, s45, v44
	s_nop 1
	v_addc_co_u32_e32 v219, vcc, 0, v45, vcc
	global_load_dwordx4 v[184:187], v[218:219], off nt
	v_add_co_u32_e32 v218, vcc, s46, v44
	s_nop 1
	v_addc_co_u32_e32 v219, vcc, 0, v45, vcc
	global_load_dwordx4 v[188:191], v[218:219], off nt
	v_add_co_u32_e32 v218, vcc, s47, v44
	s_nop 1
	v_addc_co_u32_e32 v219, vcc, 0, v45, vcc
	global_load_dwordx4 v[192:195], v[218:219], off nt
	v_add_co_u32_e32 v218, vcc, s27, v44
	s_nop 1
	v_addc_co_u32_e32 v219, vcc, 0, v45, vcc
	global_load_dwordx4 v[202:205], v[218:219], off nt
	v_add_co_u32_e32 v218, vcc, s48, v44
	s_nop 1
	v_addc_co_u32_e32 v219, vcc, 0, v45, vcc
	global_load_dwordx4 v[206:209], v[218:219], off nt
	v_add_co_u32_e32 v218, vcc, s49, v44
	s_nop 1
	v_addc_co_u32_e32 v219, vcc, 0, v45, vcc
	global_load_dwordx4 v[210:213], v[218:219], off nt
	v_add_co_u32_e32 v218, vcc, s50, v44
	s_nop 1
	v_addc_co_u32_e32 v219, vcc, 0, v45, vcc
	global_load_dwordx4 v[214:217], v[218:219], off nt
	s_waitcnt vmcnt(15)
	v_mov_b32_e32 v20, v148
	v_mov_b32_e32 v21, v149
	v_mov_b32_e32 v22, v150
	v_mov_b32_e32 v23, v151
	v_mov_b32_e32 v54, s54
	ds_read_b128 v[24:27], v54
	ds_read_b128 v[28:31], v54 offset:16
	ds_read_b128 v[32:35], v54 offset:32
	ds_read_b128 v[36:39], v54 offset:48
	ds_read_b128 v[40:43], v54 offset:128
	s_add_u32 s10, s10, 0x60000
	s_addc_u32 s11, s11, 0
	s_add_i32 s54, s54, 64
	s_cmp_eq_u32 s10, 0xc0000
	s_waitcnt lgkmcnt(4)
	v_pk_fma_f32 v[46:47], v[22:23], v[24:25], v[4:5] op_sel_hi:[1,0,1]
	v_pk_fma_f32 v[48:49], v[20:21], v[24:25], v[14:15] op_sel_hi:[1,0,1]
	s_waitcnt lgkmcnt(0)
	v_pk_fma_f32 v[50:51], v[22:23], v[40:41], v[2:3] op_sel_hi:[1,0,1]
	v_pk_fma_f32 v[52:53], v[20:21], v[40:41], v[12:13] op_sel_hi:[1,0,1]
	ds_read_b128 v[2:5], v54 offset:256
	ds_read_b128 v[12:15], v54 offset:384
	s_waitcnt lgkmcnt(1)
	v_pk_fma_f32 v[16:17], v[20:21], v[2:3], v[16:17] op_sel_hi:[1,0,1]
	s_waitcnt lgkmcnt(0)
	v_pk_fma_f32 v[10:11], v[20:21], v[12:13], v[10:11] op_sel_hi:[1,0,1]
	v_add_co_u32_e32 v20, vcc, s20, v44
	v_pk_fma_f32 v[6:7], v[22:23], v[2:3], v[6:7] op_sel_hi:[1,0,1]
	s_nop 0
	v_addc_co_u32_e32 v21, vcc, 0, v45, vcc
	v_pk_fma_f32 v[0:1], v[22:23], v[12:13], v[0:1] op_sel_hi:[1,0,1]
	s_waitcnt vmcnt(14)
	v_mov_b32_e32 v20, v152
	v_mov_b32_e32 v21, v153
	v_mov_b32_e32 v22, v154
	v_mov_b32_e32 v23, v155
	v_pk_fma_f32 v[10:11], v[20:21], v[12:13], v[10:11] op_sel:[0,1,0]
	v_pk_fma_f32 v[12:13], v[22:23], v[12:13], v[0:1] op_sel:[0,1,0]
	v_add_co_u32_e32 v0, vcc, s22, v44
	v_pk_fma_f32 v[16:17], v[20:21], v[2:3], v[16:17] op_sel:[0,1,0]
	s_nop 0
	v_addc_co_u32_e32 v1, vcc, 0, v45, vcc
	v_pk_fma_f32 v[6:7], v[22:23], v[2:3], v[6:7] op_sel:[0,1,0]
	s_waitcnt vmcnt(13)
	v_mov_b32_e32 v0, v156
	v_mov_b32_e32 v1, v157
	v_mov_b32_e32 v2, v158
	v_mov_b32_e32 v3, v159
	v_pk_fma_f32 v[48:49], v[20:21], v[24:25], v[48:49] op_sel:[0,1,0]
	v_pk_fma_f32 v[24:25], v[22:23], v[24:25], v[46:47] op_sel:[0,1,0]
	v_pk_fma_f32 v[46:47], v[20:21], v[40:41], v[52:53] op_sel:[0,1,0]
	v_pk_fma_f32 v[40:41], v[22:23], v[40:41], v[50:51] op_sel:[0,1,0]
	v_pk_fma_f32 v[20:21], v[2:3], v[26:27], v[24:25] op_sel_hi:[1,0,1]
	v_pk_fma_f32 v[22:23], v[0:1], v[26:27], v[48:49] op_sel_hi:[1,0,1]
	v_pk_fma_f32 v[24:25], v[2:3], v[42:43], v[40:41] op_sel_hi:[1,0,1]
	v_pk_fma_f32 v[40:41], v[0:1], v[42:43], v[46:47] op_sel_hi:[1,0,1]
	v_pk_fma_f32 v[16:17], v[0:1], v[4:5], v[16:17] op_sel_hi:[1,0,1]
	v_pk_fma_f32 v[10:11], v[0:1], v[14:15], v[10:11] op_sel_hi:[1,0,1]
	v_add_co_u32_e32 v0, vcc, s35, v44
	v_pk_fma_f32 v[6:7], v[2:3], v[4:5], v[6:7] op_sel_hi:[1,0,1]
	s_nop 0
	v_addc_co_u32_e32 v1, vcc, 0, v45, vcc
	v_pk_fma_f32 v[12:13], v[2:3], v[14:15], v[12:13] op_sel_hi:[1,0,1]
	s_waitcnt vmcnt(12)
	v_mov_b32_e32 v0, v160
	v_mov_b32_e32 v1, v161
	v_mov_b32_e32 v2, v162
	v_mov_b32_e32 v3, v163
	v_mov_b32_e32 v4, v27
	v_pk_fma_f32 v[20:21], v[2:3], v[4:5], v[20:21] op_sel_hi:[1,0,1]
	v_pk_fma_f32 v[22:23], v[0:1], v[4:5], v[22:23] op_sel_hi:[1,0,1]
	v_mov_b32_e32 v4, v43
	v_pk_fma_f32 v[24:25], v[2:3], v[4:5], v[24:25] op_sel_hi:[1,0,1]
	v_pk_fma_f32 v[26:27], v[0:1], v[4:5], v[40:41] op_sel_hi:[1,0,1]
	v_mov_b32_e32 v4, v5
	v_pk_fma_f32 v[40:41], v[2:3], v[4:5], v[6:7] op_sel_hi:[1,0,1]
	v_pk_fma_f32 v[16:17], v[0:1], v[4:5], v[16:17] op_sel_hi:[1,0,1]
	v_mov_b32_e32 v4, v15
	v_pk_fma_f32 v[46:47], v[0:1], v[4:5], v[10:11] op_sel_hi:[1,0,1]
	v_add_co_u32_e32 v0, vcc, s23, v44
	v_pk_fma_f32 v[42:43], v[2:3], v[4:5], v[12:13] op_sel_hi:[1,0,1]
	s_nop 0
	v_addc_co_u32_e32 v1, vcc, 0, v45, vcc
	s_waitcnt vmcnt(11)
; __device__ __forceinline__ void gemv_item(const Params& p, unsigned long long* MOD, int it, LAS float* scr, int lane) {
;     ...
;     for (int kk = 0; kk < 32; ++kk) { const f32x4 w = *(const f32x4*)(W + (size_t)kk * 6144);
;         a0 += w * scr[kk]; a1 += w * scr[32 + kk]; a2 += w * scr[64 + kk]; a3 += w * scr[96 + kk]; }
	v_mov_b32_e32 v0, v164
	v_mov_b32_e32 v1, v165
	v_mov_b32_e32 v2, v166
	v_mov_b32_e32 v3, v167
	ds_read_b128 v[4:7], v54 offset:144
	ds_read_b128 v[10:13], v54 offset:272
	s_waitcnt lgkmcnt(0)
	v_pk_fma_f32 v[48:49], v[0:1], v[10:11], v[16:17] op_sel_hi:[1,0,1]
	ds_read_b128 v[14:17], v54 offset:400
	v_pk_fma_f32 v[22:23], v[0:1], v[28:29], v[22:23] op_sel_hi:[1,0,1]
	v_pk_fma_f32 v[26:27], v[0:1], v[4:5], v[26:27] op_sel_hi:[1,0,1]
	v_pk_fma_f32 v[20:21], v[2:3], v[28:29], v[20:21] op_sel_hi:[1,0,1]
	v_pk_fma_f32 v[24:25], v[2:3], v[4:5], v[24:25] op_sel_hi:[1,0,1]
	s_waitcnt lgkmcnt(0)
	v_pk_fma_f32 v[46:47], v[0:1], v[14:15], v[46:47] op_sel_hi:[1,0,1]
	v_add_co_u32_e32 v0, vcc, s36, v44
	v_pk_fma_f32 v[40:41], v[2:3], v[10:11], v[40:41] op_sel_hi:[1,0,1]
	s_nop 0
	v_addc_co_u32_e32 v1, vcc, 0, v45, vcc
	v_pk_fma_f32 v[42:43], v[2:3], v[14:15], v[42:43] op_sel_hi:[1,0,1]
	s_waitcnt vmcnt(10)
	v_mov_b32_e32 v0, v168
	v_mov_b32_e32 v1, v169
	v_mov_b32_e32 v2, v170
	v_mov_b32_e32 v3, v171
	v_pk_fma_f32 v[20:21], v[2:3], v[28:29], v[20:21] op_sel:[0,1,0]
	v_pk_fma_f32 v[22:23], v[0:1], v[28:29], v[22:23] op_sel:[0,1,0]
	v_pk_fma_f32 v[24:25], v[2:3], v[4:5], v[24:25] op_sel:[0,1,0]
	v_pk_fma_f32 v[4:5], v[0:1], v[4:5], v[26:27] op_sel:[0,1,0]
	v_pk_fma_f32 v[26:27], v[2:3], v[10:11], v[40:41] op_sel:[0,1,0]
	v_pk_fma_f32 v[10:11], v[0:1], v[10:11], v[48:49] op_sel:[0,1,0]
	v_pk_fma_f32 v[28:29], v[2:3], v[14:15], v[42:43] op_sel:[0,1,0]
	v_pk_fma_f32 v[14:15], v[0:1], v[14:15], v[46:47] op_sel:[0,1,0]
	v_add_co_u32_e32 v0, vcc, s43, v44
	s_nop 1
	v_addc_co_u32_e32 v1, vcc, 0, v45, vcc
	s_waitcnt vmcnt(9)
	v_mov_b32_e32 v0, v172
	v_mov_b32_e32 v1, v173
	v_mov_b32_e32 v2, v174
	v_mov_b32_e32 v3, v175
	v_pk_fma_f32 v[22:23], v[0:1], v[30:31], v[22:23] op_sel_hi:[1,0,1]
	v_pk_fma_f32 v[4:5], v[0:1], v[6:7], v[4:5] op_sel_hi:[1,0,1]
	v_pk_fma_f32 v[10:11], v[0:1], v[12:13], v[10:11] op_sel_hi:[1,0,1]
	v_pk_fma_f32 v[14:15], v[0:1], v[16:17], v[14:15] op_sel_hi:[1,0,1]
	v_add_co_u32_e32 v0, vcc, s44, v44
	v_pk_fma_f32 v[20:21], v[2:3], v[30:31], v[20:21] op_sel_hi:[1,0,1]
	s_nop 0
	v_addc_co_u32_e32 v1, vcc, 0, v45, vcc
	v_pk_fma_f32 v[24:25], v[2:3], v[6:7], v[24:25] op_sel_hi:[1,0,1]
	v_pk_fma_f32 v[26:27], v[2:3], v[12:13], v[26:27] op_sel_hi:[1,0,1]
	v_pk_fma_f32 v[28:29], v[2:3], v[16:17], v[28:29] op_sel_hi:[1,0,1]
	s_waitcnt vmcnt(8)
	v_mov_b32_e32 v0, v176
	v_mov_b32_e32 v1, v177
	v_mov_b32_e32 v2, v178
	v_mov_b32_e32 v3, v179
	v_mov_b32_e32 v6, v31
	v_pk_fma_f32 v[20:21], v[2:3], v[6:7], v[20:21] op_sel_hi:[1,0,1]
	v_pk_fma_f32 v[22:23], v[0:1], v[6:7], v[22:23] op_sel_hi:[1,0,1]
	v_mov_b32_e32 v6, v7
	v_pk_fma_f32 v[30:31], v[0:1], v[6:7], v[4:5] op_sel_hi:[1,0,1]
	v_mov_b32_e32 v4, v13
	v_pk_fma_f32 v[26:27], v[2:3], v[4:5], v[26:27] op_sel_hi:[1,0,1]
	v_pk_fma_f32 v[40:41], v[0:1], v[4:5], v[10:11] op_sel_hi:[1,0,1]
	v_mov_b32_e32 v4, v17
	v_pk_fma_f32 v[42:43], v[0:1], v[4:5], v[14:15] op_sel_hi:[1,0,1]
	v_add_co_u32_e32 v0, vcc, s25, v44
	v_pk_fma_f32 v[24:25], v[2:3], v[6:7], v[24:25] op_sel_hi:[1,0,1]
	s_nop 0
	v_addc_co_u32_e32 v1, vcc, 0, v45, vcc
	v_pk_fma_f32 v[28:29], v[2:3], v[4:5], v[28:29] op_sel_hi:[1,0,1]
	s_waitcnt vmcnt(7)
	v_mov_b32_e32 v0, v180
	v_mov_b32_e32 v1, v181
	v_mov_b32_e32 v2, v182
	v_mov_b32_e32 v3, v183
	ds_read_b128 v[4:7], v54 offset:160
	ds_read_b128 v[10:13], v54 offset:288
	ds_read_b128 v[14:17], v54 offset:416
	v_pk_fma_f32 v[22:23], v[0:1], v[32:33], v[22:23] op_sel_hi:[1,0,1]
	s_waitcnt lgkmcnt(2)
	v_pk_fma_f32 v[30:31], v[0:1], v[4:5], v[30:31] op_sel_hi:[1,0,1]
	s_waitcnt lgkmcnt(1)
	v_pk_fma_f32 v[40:41], v[0:1], v[10:11], v[40:41] op_sel_hi:[1,0,1]
	s_waitcnt lgkmcnt(0)
	v_pk_fma_f32 v[42:43], v[0:1], v[14:15], v[42:43] op_sel_hi:[1,0,1]
	v_add_co_u32_e32 v0, vcc, s45, v44
	v_pk_fma_f32 v[20:21], v[2:3], v[32:33], v[20:21] op_sel_hi:[1,0,1]
	s_nop 0
	v_addc_co_u32_e32 v1, vcc, 0, v45, vcc
	v_pk_fma_f32 v[24:25], v[2:3], v[4:5], v[24:25] op_sel_hi:[1,0,1]
	v_pk_fma_f32 v[26:27], v[2:3], v[10:11], v[26:27] op_sel_hi:[1,0,1]
	v_pk_fma_f32 v[28:29], v[2:3], v[14:15], v[28:29] op_sel_hi:[1,0,1]
	s_waitcnt vmcnt(6)
	v_mov_b32_e32 v0, v184
	v_mov_b32_e32 v1, v185
	v_mov_b32_e32 v2, v186
	v_mov_b32_e32 v3, v187
	v_pk_fma_f32 v[22:23], v[0:1], v[32:33], v[22:23] op_sel:[0,1,0]
	v_pk_fma_f32 v[24:25], v[2:3], v[4:5], v[24:25] op_sel:[0,1,0]
	v_pk_fma_f32 v[4:5], v[0:1], v[4:5], v[30:31] op_sel:[0,1,0]
	v_pk_fma_f32 v[26:27], v[2:3], v[10:11], v[26:27] op_sel:[0,1,0]
	v_pk_fma_f32 v[10:11], v[0:1], v[10:11], v[40:41] op_sel:[0,1,0]
	v_pk_fma_f32 v[28:29], v[2:3], v[14:15], v[28:29] op_sel:[0,1,0]
	v_pk_fma_f32 v[14:15], v[0:1], v[14:15], v[42:43] op_sel:[0,1,0]
	v_add_co_u32_e32 v0, vcc, s46, v44
	v_pk_fma_f32 v[20:21], v[2:3], v[32:33], v[20:21] op_sel:[0,1,0]
	s_nop 0
	v_addc_co_u32_e32 v1, vcc, 0, v45, vcc
	s_waitcnt vmcnt(5)
; __device__ __forceinline__ void gemv_item(const Params& p, unsigned long long* MOD, int it, LAS float* scr, int lane) {
;     ...
;     for (int kk = 0; kk < 32; ++kk) { const f32x4 w = *(const f32x4*)(W + (size_t)kk * 6144);
;         a0 += w * scr[kk]; a1 += w * scr[32 + kk]; a2 += w * scr[64 + kk]; a3 += w * scr[96 + kk]; }
;     if (ks == 0) { const f32x4 bv = *(const f32x4*)(p.ada_b + mat * 6144 + n0); a0 += bv; a1 += bv; a2 += bv; a3 += bv; }
	v_mov_b32_e32 v0, v188
	v_mov_b32_e32 v1, v189
	v_mov_b32_e32 v2, v190
	v_mov_b32_e32 v3, v191
	v_pk_fma_f32 v[22:23], v[0:1], v[34:35], v[22:23] op_sel_hi:[1,0,1]
	v_pk_fma_f32 v[4:5], v[0:1], v[6:7], v[4:5] op_sel_hi:[1,0,1]
	v_pk_fma_f32 v[10:11], v[0:1], v[12:13], v[10:11] op_sel_hi:[1,0,1]
	v_pk_fma_f32 v[14:15], v[0:1], v[16:17], v[14:15] op_sel_hi:[1,0,1]
	v_add_co_u32_e32 v0, vcc, s47, v44
	v_pk_fma_f32 v[20:21], v[2:3], v[34:35], v[20:21] op_sel_hi:[1,0,1]
	s_nop 0
	v_addc_co_u32_e32 v1, vcc, 0, v45, vcc
	v_pk_fma_f32 v[24:25], v[2:3], v[6:7], v[24:25] op_sel_hi:[1,0,1]
	v_pk_fma_f32 v[26:27], v[2:3], v[12:13], v[26:27] op_sel_hi:[1,0,1]
	v_pk_fma_f32 v[28:29], v[2:3], v[16:17], v[28:29] op_sel_hi:[1,0,1]
	s_waitcnt vmcnt(4)
	v_mov_b32_e32 v0, v192
	v_mov_b32_e32 v1, v193
	v_mov_b32_e32 v2, v194
	v_mov_b32_e32 v3, v195
	v_mov_b32_e32 v6, v35
	v_pk_fma_f32 v[20:21], v[2:3], v[6:7], v[20:21] op_sel_hi:[1,0,1]
	v_pk_fma_f32 v[22:23], v[0:1], v[6:7], v[22:23] op_sel_hi:[1,0,1]
	v_mov_b32_e32 v6, v7
	v_pk_fma_f32 v[30:31], v[0:1], v[6:7], v[4:5] op_sel_hi:[1,0,1]
	v_mov_b32_e32 v4, v13
	v_pk_fma_f32 v[12:13], v[2:3], v[4:5], v[26:27] op_sel_hi:[1,0,1]
	v_pk_fma_f32 v[10:11], v[0:1], v[4:5], v[10:11] op_sel_hi:[1,0,1]
	v_mov_b32_e32 v4, v17
	v_pk_fma_f32 v[26:27], v[2:3], v[4:5], v[28:29] op_sel_hi:[1,0,1]
	v_pk_fma_f32 v[28:29], v[0:1], v[4:5], v[14:15] op_sel_hi:[1,0,1]
	v_add_co_u32_e32 v0, vcc, s27, v44
	v_pk_fma_f32 v[24:25], v[2:3], v[6:7], v[24:25] op_sel_hi:[1,0,1]
	s_nop 0
	v_addc_co_u32_e32 v1, vcc, 0, v45, vcc
	s_waitcnt vmcnt(3)
	v_mov_b32_e32 v0, v202
	v_mov_b32_e32 v1, v203
	v_mov_b32_e32 v2, v204
	v_mov_b32_e32 v3, v205
	ds_read_b128 v[4:7], v54 offset:176
	ds_read_b128 v[14:17], v54 offset:304
	v_pk_fma_f32 v[32:33], v[2:3], v[36:37], v[20:21] op_sel_hi:[1,0,1]
	v_pk_fma_f32 v[34:35], v[0:1], v[36:37], v[22:23] op_sel_hi:[1,0,1]
	ds_read_b128 v[20:23], v54 offset:432
	s_waitcnt lgkmcnt(2)
	v_pk_fma_f32 v[30:31], v[0:1], v[4:5], v[30:31] op_sel_hi:[1,0,1]
	s_waitcnt lgkmcnt(1)
	v_pk_fma_f32 v[10:11], v[0:1], v[14:15], v[10:11] op_sel_hi:[1,0,1]
	v_pk_fma_f32 v[24:25], v[2:3], v[4:5], v[24:25] op_sel_hi:[1,0,1]
	v_pk_fma_f32 v[12:13], v[2:3], v[14:15], v[12:13] op_sel_hi:[1,0,1]
	s_waitcnt lgkmcnt(0)
	v_pk_fma_f32 v[28:29], v[0:1], v[20:21], v[28:29] op_sel_hi:[1,0,1]
	v_add_co_u32_e32 v0, vcc, s48, v44
	v_pk_fma_f32 v[26:27], v[2:3], v[20:21], v[26:27] op_sel_hi:[1,0,1]
	s_nop 0
	v_addc_co_u32_e32 v1, vcc, 0, v45, vcc
	s_waitcnt vmcnt(2)
	v_mov_b32_e32 v0, v206
	v_mov_b32_e32 v1, v207
	v_mov_b32_e32 v2, v208
	v_mov_b32_e32 v3, v209
	v_pk_fma_f32 v[34:35], v[0:1], v[36:37], v[34:35] op_sel:[0,1,0]
	v_pk_fma_f32 v[24:25], v[2:3], v[4:5], v[24:25] op_sel:[0,1,0]
	v_pk_fma_f32 v[4:5], v[0:1], v[4:5], v[30:31] op_sel:[0,1,0]
	v_pk_fma_f32 v[12:13], v[2:3], v[14:15], v[12:13] op_sel:[0,1,0]
	v_pk_fma_f32 v[10:11], v[0:1], v[14:15], v[10:11] op_sel:[0,1,0]
	v_pk_fma_f32 v[14:15], v[2:3], v[20:21], v[26:27] op_sel:[0,1,0]
	v_pk_fma_f32 v[20:21], v[0:1], v[20:21], v[28:29] op_sel:[0,1,0]
	v_add_co_u32_e32 v0, vcc, s49, v44
	v_pk_fma_f32 v[32:33], v[2:3], v[36:37], v[32:33] op_sel:[0,1,0]
	s_nop 0
	v_addc_co_u32_e32 v1, vcc, 0, v45, vcc
	s_waitcnt vmcnt(1)
	v_mov_b32_e32 v0, v210
	v_mov_b32_e32 v1, v211
	v_mov_b32_e32 v2, v212
	v_mov_b32_e32 v3, v213
	v_pk_fma_f32 v[30:31], v[0:1], v[38:39], v[34:35] op_sel_hi:[1,0,1]
	v_pk_fma_f32 v[34:35], v[0:1], v[6:7], v[4:5] op_sel_hi:[1,0,1]
	v_pk_fma_f32 v[10:11], v[0:1], v[16:17], v[10:11] op_sel_hi:[1,0,1]
	v_pk_fma_f32 v[20:21], v[0:1], v[22:23], v[20:21] op_sel_hi:[1,0,1]
	v_add_co_u32_e32 v0, vcc, s50, v44
	v_pk_fma_f32 v[28:29], v[2:3], v[38:39], v[32:33] op_sel_hi:[1,0,1]
	s_nop 0
	v_addc_co_u32_e32 v1, vcc, 0, v45, vcc
	v_pk_fma_f32 v[32:33], v[2:3], v[6:7], v[24:25] op_sel_hi:[1,0,1]
	s_waitcnt vmcnt(0)
	v_mov_b32_e32 v24, v214
	v_mov_b32_e32 v25, v215
	v_mov_b32_e32 v26, v216
	v_mov_b32_e32 v27, v217
	v_mov_b32_e32 v0, v39
	v_pk_fma_f32 v[40:41], v[2:3], v[22:23], v[14:15] op_sel_hi:[1,0,1]
	v_pk_fma_f32 v[36:37], v[2:3], v[16:17], v[12:13] op_sel_hi:[1,0,1]
	v_pk_fma_f32 v[4:5], v[26:27], v[0:1], v[28:29] op_sel_hi:[1,0,1]
	v_pk_fma_f32 v[14:15], v[24:25], v[0:1], v[30:31] op_sel_hi:[1,0,1]
	v_mov_b32_e32 v0, v7
	v_pk_fma_f32 v[2:3], v[26:27], v[0:1], v[32:33] op_sel_hi:[1,0,1]
	v_pk_fma_f32 v[12:13], v[24:25], v[0:1], v[34:35] op_sel_hi:[1,0,1]
	v_mov_b32_e32 v0, v17
	v_pk_fma_f32 v[16:17], v[24:25], v[0:1], v[10:11] op_sel_hi:[1,0,1]
	v_mov_b32_e32 v10, v23
	v_pk_fma_f32 v[6:7], v[26:27], v[0:1], v[36:37] op_sel_hi:[1,0,1]
	v_pk_fma_f32 v[0:1], v[26:27], v[10:11], v[40:41] op_sel_hi:[1,0,1]
	v_pk_fma_f32 v[10:11], v[24:25], v[10:11], v[20:21] op_sel_hi:[1,0,1]
	s_cbranch_scc0 .LBB0_61
	s_cmp_eq_u32 s53, 0
	s_cbranch_scc0 .LBB0_29
	s_mul_i32 s0, s2, 0x1800
	s_ashr_i32 s1, s0, 31
	s_lshl_b64 s[0:1], s[0:1], 2
	s_add_u32 s0, s86, s0
	s_addc_u32 s1, s87, s1
	v_lshl_add_u64 v[18:19], v[8:9], 2, s[0:1]
	global_load_dwordx4 v[18:21], v[18:19], off
	s_waitcnt vmcnt(0)
	v_pk_add_f32 v[4:5], v[4:5], v[20:21]
	v_pk_add_f32 v[14:15], v[14:15], v[18:19]
	v_pk_add_f32 v[2:3], v[2:3], v[20:21]
	v_pk_add_f32 v[12:13], v[12:13], v[18:19]
	v_pk_add_f32 v[6:7], v[6:7], v[20:21]
	v_pk_add_f32 v[16:17], v[16:17], v[18:19]
	v_pk_add_f32 v[0:1], v[0:1], v[20:21]
	v_pk_add_f32 v[10:11], v[10:11], v[18:19]
	s_branch .LBB0_29
